# norm phases (NORM2 all layers, NORM1 layers 1-3): hand-written latent-row loop, 4-deep row prefetch, LDS param table, contiguous rows per wave, write-through (sc1) H stores; on top of FFN1 epilogue +
# speedup vs baseline: 1.0293x; 1.0146x over previous
; __device__ __forceinline__ f32x4 bf4_to_f32(u32x2 w) { return (f32x4){__builtin_bit_cast(float, w.x << 16), __builtin_bit_cast(float, w.x & 0xffff0000u), __builtin_bit_cast(float, w.y << 16), __builtin_bit_cast(float, w.y & 0xffff0000u)}; }
; __device__ __forceinline__ void norm_phase(const Params& P, unsigned char* ws, int layer, int which, int nrows, bool first, int lane, int wave, const float* pend_part, int pend_ns, const float* pend_gate) {
;     ...
;     bf16_t* XB = (bf16_t*)((unsigned char*)P.out + XB_OFF);
;     for (int row0 = gw; row0 < MLAT; row0 += NR * NGW) {
;         f32x4 v[NR][2][2]; float ss[NR];
; #pragma unroll
;         for (int r = 0; r < NR; ++r) { const int row = row0 + r * NGW; ss[r] = 0.f;
; #pragma unroll
;             for (int j = 0; j < 2; ++j) { const int col = 8 * lane + 512 * j;
;                 if (first) { v[r][j][0] = *(const f32x4*)(P.in[I_X] + (size_t)row * DM + col); v[r][j][1] = *(const f32x4*)(P.in[I_X] + (size_t)row * DM + col + 4); }
;                 else { const u32x4 w = *(const u32x4*)(XB + (size_t)row * DM + col); v[r][j][0] = bf4_to_f32((u32x2){w.x, w.y}); v[r][j][1] = bf4_to_f32((u32x2){w.z, w.w}); } } }
; #pragma unroll
;         for (int r = 0; r < NR; ++r)
; #pragma unroll
;             for (int j = 0; j < 2; ++j)
; #pragma unroll
;                 for (int q = 0; q < 2; ++q) ss[r] += (v[r][j][q][0] * v[r][j][q][0] + v[r][j][q][1] * v[r][j][q][1]) + (v[r][j][q][2] * v[r][j][q][2] + v[r][j][q][3] * v[r][j][q][3]);
; #pragma unroll
;         for (int r = 0; r < NR; ++r) { const int row = row0 + r * NGW;
;             const float rstd = rsqrtf(wave_sum(ss[r], lane) * (1.0f / DM) + EPS);
;             const float* mod = (const float*)(ws + WS_MOD) + (size_t)(layer * 9 + (row >> 12)) * 6144 + which * 3 * DM;
; #pragma unroll
;             for (int j = 0; j < 2; ++j) { const int col = 8 * lane + 512 * j; u32x4 hw, xw;
; #pragma unroll
;                 for (int q = 0; q < 2; ++q) {
;                     const f32x4 g4 = *(const f32x4*)(g + col + 4 * q), sh = *(const f32x4*)(mod + col + 4 * q), sc = *(const f32x4*)(mod + DM + col + 4 * q);
.LBB0_906:
	s_cmpk_gt_i32 s2, 0x7fff
	s_mov_b32 s14, 0x800000
	s_mov_b32 s19, 0x6400000
	s_cbranch_scc1 .LBB0_909
	s_cmp_eq_u32 s88, 0x800
	s_cbranch_scc0 .Lmy_n2_old
	s_add_u32 s8, s20, 0x803000
	s_addc_u32 s9, s21, 0
	s_mov_b32 s99, 0
.Lmy_norm_entry:
	s_waitcnt vmcnt(0) lgkmcnt(0)
	s_barrier
	v_readlane_b32 s48, v251, 10
	v_readlane_b32 s49, v251, 11
	v_readlane_b32 s50, v251, 12
	v_readlane_b32 s51, v251, 13
	v_readlane_b32 s52, v251, 14
	v_readlane_b32 s53, v251, 15
	v_readlane_b32 s54, v251, 16
	v_readlane_b32 s55, v251, 17
	v_readlane_b32 s56, v251, 18
	v_readlane_b32 s57, v251, 19
	v_readlane_b32 s58, v251, 20
	v_readlane_b32 s59, v251, 21
	v_readlane_b32 s60, v251, 22
	v_readlane_b32 s61, v251, 23
	v_readlane_b32 s62, v251, 24
	v_readlane_b32 s63, v251, 25
	s_add_u32 s22, s62, 0x4000000
	s_addc_u32 s23, s63, 0
	s_add_u32 s26, s20, 0x6400000
	s_addc_u32 s27, s21, 0
	v_lshlrev_b32_e32 v2, 4, v221
	v_lshlrev_b32_e32 v3, 5, v221
	v_lshlrev_b32_e32 v0, 2, v221
	s_lshl_b32 s98, s2, 4
	s_lshr_b32 s10, s2, 8
	s_lshl_b32 s10, s10, 12
	v_add_u32_e32 v15, s10, v3
	v_xor_b32_e32 v5, 4, v0
	v_xor_b32_e32 v6, 8, v0
	v_xor_b32_e32 v7, 16, v0
	v_xor_b32_e32 v9, 32, v0
	v_xor_b32_e32 v10, 64, v0
	v_xor_b32_e32 v11, 0x80, v0
	v_and_b32_e32 v13, 0xff, v196
	v_lshlrev_b32_e32 v13, 4, v13
	v_lshrrev_b32_e32 v14, 8, v196
	v_mul_u32_u24_e32 v14, 0x6000, v14
	v_add_u32_e32 v13, v13, v14
	v_lshlrev_b32_e32 v14, 4, v196
	s_mul_i32 s10, s12, 0x6000
	s_add_u32 s0, s8, s10
	s_addc_u32 s1, s9, 0
	s_add_u32 s30, s0, 0x1000
	s_addc_u32 s31, s1, 0
	global_load_dwordx4 v[128:131], v13, s[0:1]
	s_add_u32 s0, s0, 0xc000
	s_addc_u32 s1, s1, 0
	global_load_dwordx4 v[132:135], v13, s[0:1]
	s_add_u32 s0, s0, 0xc000
	s_addc_u32 s1, s1, 0
	global_load_dwordx4 v[136:139], v13, s[0:1]
	s_add_u32 s0, s0, 0xc000
	s_addc_u32 s1, s1, 0
	global_load_dwordx4 v[140:143], v13, s[0:1]
	global_load_dwordx4 v[144:147], v13, s[30:31]
	s_add_u32 s30, s30, 0xc000
	s_addc_u32 s31, s31, 0
	global_load_dwordx4 v[148:151], v13, s[30:31]
	s_add_u32 s30, s30, 0xc000
	s_addc_u32 s31, s31, 0
	global_load_dwordx4 v[152:155], v13, s[30:31]
	s_add_u32 s30, s30, 0xc000
	s_addc_u32 s31, s31, 0
	global_load_dwordx4 v[156:159], v13, s[30:31]
	global_load_dwordx4 v[16:19], v3, s[24:25]
	global_load_dwordx4 v[20:23], v3, s[24:25] offset:16
	global_load_dwordx4 v[24:27], v3, s[24:25] offset:2048
	global_load_dwordx4 v[28:31], v3, s[24:25] offset:2064
	s_mov_b32 s10, s98
	s_lshl_b32 s10, s10, 11
	s_add_u32 s28, s22, s10
	s_addc_u32 s29, s23, 0
	global_load_dwordx4 v[64:67], v2, s[28:29]
	global_load_dwordx4 v[68:71], v2, s[28:29] offset:1024
	s_add_i32 s10, s98, 0x1
	s_lshl_b32 s10, s10, 11
	s_add_u32 s28, s22, s10
	s_addc_u32 s29, s23, 0
	global_load_dwordx4 v[72:75], v2, s[28:29]
	global_load_dwordx4 v[76:79], v2, s[28:29] offset:1024
	s_add_i32 s10, s98, 0x2
	s_lshl_b32 s10, s10, 11
	s_add_u32 s28, s22, s10
	s_addc_u32 s29, s23, 0
	global_load_dwordx4 v[80:83], v2, s[28:29]
	global_load_dwordx4 v[84:87], v2, s[28:29] offset:1024
	s_add_i32 s10, s98, 0x3
	s_lshl_b32 s10, s10, 11
	s_add_u32 s28, s22, s10
	s_addc_u32 s29, s23, 0
	global_load_dwordx4 v[88:91], v2, s[28:29]
	global_load_dwordx4 v[92:95], v2, s[28:29] offset:1024
	s_add_i32 s10, s98, 0x4
	s_lshl_b32 s10, s10, 11
	s_add_u32 s28, s22, s10
	s_addc_u32 s29, s23, 0
	global_load_dwordx4 v[96:99], v2, s[28:29]
	global_load_dwordx4 v[100:103], v2, s[28:29] offset:1024
	s_add_i32 s10, s98, 0x5
	s_lshl_b32 s10, s10, 11
	s_add_u32 s28, s22, s10
	s_addc_u32 s29, s23, 0
	global_load_dwordx4 v[104:107], v2, s[28:29]
	global_load_dwordx4 v[108:111], v2, s[28:29] offset:1024
	s_add_i32 s10, s98, 0x6
	s_lshl_b32 s10, s10, 11
	s_add_u32 s28, s22, s10
	s_addc_u32 s29, s23, 0
	global_load_dwordx4 v[112:115], v2, s[28:29]
	global_load_dwordx4 v[116:119], v2, s[28:29] offset:1024
	s_add_i32 s10, s98, 0x7
	s_lshl_b32 s10, s10, 11
	s_add_u32 s28, s22, s10
	s_addc_u32 s29, s23, 0
	global_load_dwordx4 v[120:123], v2, s[28:29]
	global_load_dwordx4 v[124:127], v2, s[28:29] offset:1024
	s_waitcnt vmcnt(20)
	ds_write_b128 v14, v[128:131]
	ds_write_b128 v14, v[132:135] offset:8192
	ds_write_b128 v14, v[136:139] offset:16384
	ds_write_b128 v14, v[140:143] offset:24576
	ds_write_b128 v14, v[144:147] offset:32768
	ds_write_b128 v14, v[148:151] offset:40960
	ds_write_b128 v14, v[152:155] offset:49152
	ds_write_b128 v14, v[156:159] offset:57344
	s_waitcnt lgkmcnt(0)
	s_barrier
; __device__ __forceinline__ unsigned cvt_pk_bf16(float lo, float hi) { unsigned r; asm volatile("v_cvt_pk_bf16_f32 %0, %1, %2" : "=v"(r) : "v"(lo), "v"(hi)); return r; }
; __device__ __forceinline__ void norm_phase(const Params& P, unsigned char* ws, int layer, int which, int nrows, bool first, int lane, int wave, const float* pend_part, int pend_ns, const float* pend_gate) {
;     ...
; #pragma unroll
;         for (int r = 0; r < NR; ++r)
; #pragma unroll
;             for (int j = 0; j < 2; ++j)
; #pragma unroll
;                 for (int q = 0; q < 2; ++q) ss[r] += (v[r][j][q][0] * v[r][j][q][0] + v[r][j][q][1] * v[r][j][q][1]) + (v[r][j][q][2] * v[r][j][q][2] + v[r][j][q][3] * v[r][j][q][3]);
; #pragma unroll
;         for (int r = 0; r < NR; ++r) { const int row = row0 + r * NGW;
;             const float rstd = rsqrtf(wave_sum(ss[r], lane) * (1.0f / DM) + EPS);
;             const float* mod = (const float*)(ws + WS_MOD) + (size_t)(layer * 9 + (row >> 12)) * 6144 + which * 3 * DM;
; #pragma unroll
;             for (int j = 0; j < 2; ++j) { const int col = 8 * lane + 512 * j; u32x4 hw, xw;
; #pragma unroll
;                 for (int q = 0; q < 2; ++q) {
;                     const f32x4 g4 = *(const f32x4*)(g + col + 4 * q), sh = *(const f32x4*)(mod + col + 4 * q), sc = *(const f32x4*)(mod + DM + col + 4 * q);
;                     const f32x4 h = (v[r][j][q] * rstd) * g4 * (sc + 1.0f) + sh;
;                     if (q == 0) { hw.x = cvt_pk_bf16(h[0], h[1]); hw.y = cvt_pk_bf16(h[2], h[3]); xw.x = cvt_pk_bf16(v[r][j][q][0], v[r][j][q][1]); xw.y = cvt_pk_bf16(v[r][j][q][2], v[r][j][q][3]); }
;                     else { hw.z = cvt_pk_bf16(h[0], h[1]); hw.w = cvt_pk_bf16(h[2], h[3]); xw.z = cvt_pk_bf16(v[r][j][q][0], v[r][j][q][1]); xw.w = cvt_pk_bf16(v[r][j][q][2], v[r][j][q][3]); }
;                 }
;                 *(u32x4*)(H + (size_t)row * DM + col) = hw;
	s_waitcnt vmcnt(12)
	ds_read_b128 v[32:35], v15 offset:0
	ds_read_b128 v[36:39], v15 offset:16
	ds_read_b128 v[40:43], v15 offset:2048
	ds_read_b128 v[44:47], v15 offset:2064
	ds_read_b128 v[48:51], v15 offset:32768
	ds_read_b128 v[52:55], v15 offset:32784
	ds_read_b128 v[56:59], v15 offset:34816
	ds_read_b128 v[60:63], v15 offset:34832
	v_lshlrev_b32_e32 v128, 16, v64
	v_and_b32_e32 v129, 0xffff0000, v64
	v_lshlrev_b32_e32 v130, 16, v65
	v_and_b32_e32 v131, 0xffff0000, v65
	v_lshlrev_b32_e32 v132, 16, v66
	v_and_b32_e32 v133, 0xffff0000, v66
	v_lshlrev_b32_e32 v134, 16, v67
	v_and_b32_e32 v135, 0xffff0000, v67
	v_lshlrev_b32_e32 v136, 16, v68
	v_and_b32_e32 v137, 0xffff0000, v68
	v_lshlrev_b32_e32 v138, 16, v69
	v_and_b32_e32 v139, 0xffff0000, v69
	v_lshlrev_b32_e32 v140, 16, v70
	v_and_b32_e32 v141, 0xffff0000, v70
	v_lshlrev_b32_e32 v142, 16, v71
	v_and_b32_e32 v143, 0xffff0000, v71
	v_lshlrev_b32_e32 v144, 16, v72
	v_and_b32_e32 v145, 0xffff0000, v72
	v_lshlrev_b32_e32 v146, 16, v73
	v_and_b32_e32 v147, 0xffff0000, v73
	v_lshlrev_b32_e32 v148, 16, v74
	v_and_b32_e32 v149, 0xffff0000, v74
	v_lshlrev_b32_e32 v150, 16, v75
	v_and_b32_e32 v151, 0xffff0000, v75
	v_lshlrev_b32_e32 v152, 16, v76
	v_and_b32_e32 v153, 0xffff0000, v76
	v_lshlrev_b32_e32 v154, 16, v77
	v_and_b32_e32 v155, 0xffff0000, v77
	v_lshlrev_b32_e32 v156, 16, v78
	v_and_b32_e32 v157, 0xffff0000, v78
	v_lshlrev_b32_e32 v158, 16, v79
	v_and_b32_e32 v159, 0xffff0000, v79
	v_pk_mul_f32 v[160:161], v[128:129], v[128:129]
	v_pk_mul_f32 v[162:163], v[144:145], v[144:145]
	v_pk_fma_f32 v[160:161], v[130:131], v[130:131], v[160:161]
	v_pk_fma_f32 v[162:163], v[146:147], v[146:147], v[162:163]
	v_pk_fma_f32 v[160:161], v[132:133], v[132:133], v[160:161]
	v_pk_fma_f32 v[162:163], v[148:149], v[148:149], v[162:163]
	v_pk_fma_f32 v[160:161], v[134:135], v[134:135], v[160:161]
	v_pk_fma_f32 v[162:163], v[150:151], v[150:151], v[162:163]
	v_pk_fma_f32 v[160:161], v[136:137], v[136:137], v[160:161]
	v_pk_fma_f32 v[162:163], v[152:153], v[152:153], v[162:163]
	v_pk_fma_f32 v[160:161], v[138:139], v[138:139], v[160:161]
	v_pk_fma_f32 v[162:163], v[154:155], v[154:155], v[162:163]
	v_pk_fma_f32 v[160:161], v[140:141], v[140:141], v[160:161]
	v_pk_fma_f32 v[162:163], v[156:157], v[156:157], v[162:163]
	v_pk_fma_f32 v[160:161], v[142:143], v[142:143], v[160:161]
	v_pk_fma_f32 v[162:163], v[158:159], v[158:159], v[162:163]
	v_add_f32_e32 v160, v160, v161
	v_add_f32_e32 v162, v162, v163
	ds_bpermute_b32 v164, v5, v160
	ds_bpermute_b32 v165, v5, v162
	s_waitcnt lgkmcnt(0)
	v_add_f32_e32 v160, v160, v164
	v_add_f32_e32 v162, v162, v165
	ds_bpermute_b32 v164, v6, v160
	ds_bpermute_b32 v165, v6, v162
	s_waitcnt lgkmcnt(0)
	v_add_f32_e32 v160, v160, v164
	v_add_f32_e32 v162, v162, v165
	ds_bpermute_b32 v164, v7, v160
	ds_bpermute_b32 v165, v7, v162
	s_waitcnt lgkmcnt(0)
	v_add_f32_e32 v160, v160, v164
	v_add_f32_e32 v162, v162, v165
	ds_bpermute_b32 v164, v9, v160
	ds_bpermute_b32 v165, v9, v162
	s_waitcnt lgkmcnt(0)
	v_add_f32_e32 v160, v160, v164
	v_add_f32_e32 v162, v162, v165
	ds_bpermute_b32 v164, v10, v160
	ds_bpermute_b32 v165, v10, v162
	s_waitcnt lgkmcnt(0)
	v_add_f32_e32 v160, v160, v164
	v_add_f32_e32 v162, v162, v165
	ds_bpermute_b32 v164, v11, v160
	ds_bpermute_b32 v165, v11, v162
	s_waitcnt lgkmcnt(0)
	v_add_f32_e32 v160, v160, v164
	v_add_f32_e32 v162, v162, v165
	v_fmamk_f32 v160, v160, 0x3a800000, v194
	v_fmamk_f32 v162, v162, 0x3a800000, v194
	v_rsq_f32_e32 v160, v160
	v_rsq_f32_e32 v162, v162
	v_pk_add_f32 v[48:49], v[48:49], 1.0 op_sel_hi:[1,0]
	v_pk_add_f32 v[50:51], v[50:51], 1.0 op_sel_hi:[1,0]
	v_pk_add_f32 v[52:53], v[52:53], 1.0 op_sel_hi:[1,0]
	v_pk_add_f32 v[54:55], v[54:55], 1.0 op_sel_hi:[1,0]
	v_pk_add_f32 v[56:57], v[56:57], 1.0 op_sel_hi:[1,0]
	v_pk_add_f32 v[58:59], v[58:59], 1.0 op_sel_hi:[1,0]
	v_pk_add_f32 v[60:61], v[60:61], 1.0 op_sel_hi:[1,0]
	v_pk_add_f32 v[62:63], v[62:63], 1.0 op_sel_hi:[1,0]
	v_pk_mul_f32 v[128:129], v[160:161], v[128:129] op_sel_hi:[0,1]
	v_pk_mul_f32 v[130:131], v[160:161], v[130:131] op_sel_hi:[0,1]
	v_pk_mul_f32 v[132:133], v[160:161], v[132:133] op_sel_hi:[0,1]
	v_pk_mul_f32 v[134:135], v[160:161], v[134:135] op_sel_hi:[0,1]
	v_pk_mul_f32 v[136:137], v[160:161], v[136:137] op_sel_hi:[0,1]
	v_pk_mul_f32 v[138:139], v[160:161], v[138:139] op_sel_hi:[0,1]
	v_pk_mul_f32 v[140:141], v[160:161], v[140:141] op_sel_hi:[0,1]
	v_pk_mul_f32 v[142:143], v[160:161], v[142:143] op_sel_hi:[0,1]
	v_pk_mul_f32 v[128:129], v[16:17], v[128:129]
	v_pk_mul_f32 v[130:131], v[18:19], v[130:131]
	v_pk_mul_f32 v[132:133], v[20:21], v[132:133]
	v_pk_mul_f32 v[134:135], v[22:23], v[134:135]
	v_pk_mul_f32 v[136:137], v[24:25], v[136:137]
	v_pk_mul_f32 v[138:139], v[26:27], v[138:139]
	v_pk_mul_f32 v[140:141], v[28:29], v[140:141]
	v_pk_mul_f32 v[142:143], v[30:31], v[142:143]
	v_pk_fma_f32 v[128:129], v[48:49], v[128:129], v[32:33]
	v_pk_fma_f32 v[130:131], v[50:51], v[130:131], v[34:35]
	v_pk_fma_f32 v[132:133], v[52:53], v[132:133], v[36:37]
	v_pk_fma_f32 v[134:135], v[54:55], v[134:135], v[38:39]
	v_pk_fma_f32 v[136:137], v[56:57], v[136:137], v[40:41]
	v_pk_fma_f32 v[138:139], v[58:59], v[138:139], v[42:43]
	v_pk_fma_f32 v[140:141], v[60:61], v[140:141], v[44:45]
	v_pk_fma_f32 v[142:143], v[62:63], v[142:143], v[46:47]
	v_cvt_pk_bf16_f32 v176, v128, v129
	v_cvt_pk_bf16_f32 v177, v130, v131
	v_cvt_pk_bf16_f32 v178, v132, v133
	v_cvt_pk_bf16_f32 v179, v134, v135
	v_cvt_pk_bf16_f32 v180, v136, v137
	v_cvt_pk_bf16_f32 v181, v138, v139
	v_cvt_pk_bf16_f32 v182, v140, v141
	v_cvt_pk_bf16_f32 v183, v142, v143
	s_mov_b32 s10, s98
	s_lshl_b32 s10, s10, 11
; __device__ __forceinline__ void norm_phase(const Params& P, unsigned char* ws, int layer, int which, int nrows, bool first, int lane, int wave, const float* pend_part, int pend_ns, const float* pend_gate) {
;     ...
;         for (int r = 0; r < NR; ++r) { const int row = row0 + r * NGW; ss[r] = 0.f;
; #pragma unroll
;             for (int j = 0; j < 2; ++j) { const int col = 8 * lane + 512 * j;
;                 if (first) { v[r][j][0] = *(const f32x4*)(P.in[I_X] + (size_t)row * DM + col); v[r][j][1] = *(const f32x4*)(P.in[I_X] + (size_t)row * DM + col + 4); }
;                 else { const u32x4 w = *(const u32x4*)(XB + (size_t)row * DM + col); v[r][j][0] = bf4_to_f32((u32x2){w.x, w.y}); v[r][j][1] = bf4_to_f32((u32x2){w.z, w.w}); } } }
; #pragma unroll
;         for (int r = 0; r < NR; ++r)
; #pragma unroll
;             for (int j = 0; j < 2; ++j)
; #pragma unroll
;                 for (int q = 0; q < 2; ++q) ss[r] += (v[r][j][q][0] * v[r][j][q][0] + v[r][j][q][1] * v[r][j][q][1]) + (v[r][j][q][2] * v[r][j][q][2] + v[r][j][q][3] * v[r][j][q][3]);
; #pragma unroll
;         for (int r = 0; r < NR; ++r) { const int row = row0 + r * NGW;
;             const float rstd = rsqrtf(wave_sum(ss[r], lane) * (1.0f / DM) + EPS);
;             const float* mod = (const float*)(ws + WS_MOD) + (size_t)(layer * 9 + (row >> 12)) * 6144 + which * 3 * DM;
; #pragma unroll
;             for (int j = 0; j < 2; ++j) { const int col = 8 * lane + 512 * j; u32x4 hw, xw;
; #pragma unroll
;                 for (int q = 0; q < 2; ++q) {
;                     const f32x4 g4 = *(const f32x4*)(g + col + 4 * q), sh = *(const f32x4*)(mod + col + 4 * q), sc = *(const f32x4*)(mod + DM + col + 4 * q);
;                     const f32x4 h = (v[r][j][q] * rstd) * g4 * (sc + 1.0f) + sh;
;                     if (q == 0) { hw.x = cvt_pk_bf16(h[0], h[1]); hw.y = cvt_pk_bf16(h[2], h[3]); xw.x = cvt_pk_bf16(v[r][j][q][0], v[r][j][q][1]); xw.y = cvt_pk_bf16(v[r][j][q][2], v[r][j][q][3]); }
;                     else { hw.z = cvt_pk_bf16(h[0], h[1]); hw.w = cvt_pk_bf16(h[2], h[3]); xw.z = cvt_pk_bf16(v[r][j][q][0], v[r][j][q][1]); xw.w = cvt_pk_bf16(v[r][j][q][2], v[r][j][q][3]); }
;                 }
;                 *(u32x4*)(H + (size_t)row * DM + col) = hw;
	s_add_u32 s28, s26, s10
	s_addc_u32 s29, s27, 0
	global_store_dwordx4 v2, v[176:179], s[28:29] sc1
	global_store_dwordx4 v2, v[180:183], s[28:29] offset:1024 sc1
	v_pk_mul_f32 v[144:145], v[162:163], v[144:145] op_sel_hi:[0,1]
	v_pk_mul_f32 v[146:147], v[162:163], v[146:147] op_sel_hi:[0,1]
	v_pk_mul_f32 v[148:149], v[162:163], v[148:149] op_sel_hi:[0,1]
	v_pk_mul_f32 v[150:151], v[162:163], v[150:151] op_sel_hi:[0,1]
	v_pk_mul_f32 v[152:153], v[162:163], v[152:153] op_sel_hi:[0,1]
	v_pk_mul_f32 v[154:155], v[162:163], v[154:155] op_sel_hi:[0,1]
	v_pk_mul_f32 v[156:157], v[162:163], v[156:157] op_sel_hi:[0,1]
	v_pk_mul_f32 v[158:159], v[162:163], v[158:159] op_sel_hi:[0,1]
	v_pk_mul_f32 v[144:145], v[16:17], v[144:145]
	v_pk_mul_f32 v[146:147], v[18:19], v[146:147]
	v_pk_mul_f32 v[148:149], v[20:21], v[148:149]
	v_pk_mul_f32 v[150:151], v[22:23], v[150:151]
	v_pk_mul_f32 v[152:153], v[24:25], v[152:153]
	v_pk_mul_f32 v[154:155], v[26:27], v[154:155]
	v_pk_mul_f32 v[156:157], v[28:29], v[156:157]
	v_pk_mul_f32 v[158:159], v[30:31], v[158:159]
	v_pk_fma_f32 v[144:145], v[48:49], v[144:145], v[32:33]
	v_pk_fma_f32 v[146:147], v[50:51], v[146:147], v[34:35]
	v_pk_fma_f32 v[148:149], v[52:53], v[148:149], v[36:37]
	v_pk_fma_f32 v[150:151], v[54:55], v[150:151], v[38:39]
	v_pk_fma_f32 v[152:153], v[56:57], v[152:153], v[40:41]
	v_pk_fma_f32 v[154:155], v[58:59], v[154:155], v[42:43]
	v_pk_fma_f32 v[156:157], v[60:61], v[156:157], v[44:45]
	v_pk_fma_f32 v[158:159], v[62:63], v[158:159], v[46:47]
	v_cvt_pk_bf16_f32 v184, v144, v145
	v_cvt_pk_bf16_f32 v185, v146, v147
	v_cvt_pk_bf16_f32 v186, v148, v149
	v_cvt_pk_bf16_f32 v187, v150, v151
	v_cvt_pk_bf16_f32 v188, v152, v153
	v_cvt_pk_bf16_f32 v189, v154, v155
	v_cvt_pk_bf16_f32 v190, v156, v157
	v_cvt_pk_bf16_f32 v191, v158, v159
	s_add_i32 s10, s98, 0x1
	s_lshl_b32 s10, s10, 11
	s_add_u32 s28, s26, s10
	s_addc_u32 s29, s27, 0
	global_store_dwordx4 v2, v[184:187], s[28:29] sc1
	global_store_dwordx4 v2, v[188:191], s[28:29] offset:1024 sc1
	s_add_i32 s10, s98, 0x8
	s_lshl_b32 s10, s10, 11
	s_add_u32 s28, s22, s10
	s_addc_u32 s29, s23, 0
	global_load_dwordx4 v[64:67], v2, s[28:29]
	global_load_dwordx4 v[68:71], v2, s[28:29] offset:1024
	s_add_i32 s10, s98, 0x9
	s_lshl_b32 s10, s10, 11
	s_add_u32 s28, s22, s10
	s_addc_u32 s29, s23, 0
	global_load_dwordx4 v[72:75], v2, s[28:29]
	global_load_dwordx4 v[76:79], v2, s[28:29] offset:1024
	s_waitcnt vmcnt(16)
	ds_read_b128 v[32:35], v15 offset:0
	ds_read_b128 v[36:39], v15 offset:16
	ds_read_b128 v[40:43], v15 offset:2048
	ds_read_b128 v[44:47], v15 offset:2064
	ds_read_b128 v[48:51], v15 offset:32768
	ds_read_b128 v[52:55], v15 offset:32784
	ds_read_b128 v[56:59], v15 offset:34816
	ds_read_b128 v[60:63], v15 offset:34832
	v_lshlrev_b32_e32 v128, 16, v80
	v_and_b32_e32 v129, 0xffff0000, v80
	v_lshlrev_b32_e32 v130, 16, v81
	v_and_b32_e32 v131, 0xffff0000, v81
	v_lshlrev_b32_e32 v132, 16, v82
	v_and_b32_e32 v133, 0xffff0000, v82
	v_lshlrev_b32_e32 v134, 16, v83
	v_and_b32_e32 v135, 0xffff0000, v83
	v_lshlrev_b32_e32 v136, 16, v84
	v_and_b32_e32 v137, 0xffff0000, v84
	v_lshlrev_b32_e32 v138, 16, v85
	v_and_b32_e32 v139, 0xffff0000, v85
	v_lshlrev_b32_e32 v140, 16, v86
	v_and_b32_e32 v141, 0xffff0000, v86
	v_lshlrev_b32_e32 v142, 16, v87
	v_and_b32_e32 v143, 0xffff0000, v87
	v_lshlrev_b32_e32 v144, 16, v88
	v_and_b32_e32 v145, 0xffff0000, v88
	v_lshlrev_b32_e32 v146, 16, v89
	v_and_b32_e32 v147, 0xffff0000, v89
	v_lshlrev_b32_e32 v148, 16, v90
	v_and_b32_e32 v149, 0xffff0000, v90
	v_lshlrev_b32_e32 v150, 16, v91
	v_and_b32_e32 v151, 0xffff0000, v91
	v_lshlrev_b32_e32 v152, 16, v92
	v_and_b32_e32 v153, 0xffff0000, v92
	v_lshlrev_b32_e32 v154, 16, v93
	v_and_b32_e32 v155, 0xffff0000, v93
	v_lshlrev_b32_e32 v156, 16, v94
	v_and_b32_e32 v157, 0xffff0000, v94
	v_lshlrev_b32_e32 v158, 16, v95
	v_and_b32_e32 v159, 0xffff0000, v95
	v_pk_mul_f32 v[160:161], v[128:129], v[128:129]
	v_pk_mul_f32 v[162:163], v[144:145], v[144:145]
	v_pk_fma_f32 v[160:161], v[130:131], v[130:131], v[160:161]
	v_pk_fma_f32 v[162:163], v[146:147], v[146:147], v[162:163]
	v_pk_fma_f32 v[160:161], v[132:133], v[132:133], v[160:161]
	v_pk_fma_f32 v[162:163], v[148:149], v[148:149], v[162:163]
	v_pk_fma_f32 v[160:161], v[134:135], v[134:135], v[160:161]
	v_pk_fma_f32 v[162:163], v[150:151], v[150:151], v[162:163]
	v_pk_fma_f32 v[160:161], v[136:137], v[136:137], v[160:161]
	v_pk_fma_f32 v[162:163], v[152:153], v[152:153], v[162:163]
	v_pk_fma_f32 v[160:161], v[138:139], v[138:139], v[160:161]
	v_pk_fma_f32 v[162:163], v[154:155], v[154:155], v[162:163]
	v_pk_fma_f32 v[160:161], v[140:141], v[140:141], v[160:161]
	v_pk_fma_f32 v[162:163], v[156:157], v[156:157], v[162:163]
	v_pk_fma_f32 v[160:161], v[142:143], v[142:143], v[160:161]
	v_pk_fma_f32 v[162:163], v[158:159], v[158:159], v[162:163]
	v_add_f32_e32 v160, v160, v161
	v_add_f32_e32 v162, v162, v163
	ds_bpermute_b32 v164, v5, v160
	ds_bpermute_b32 v165, v5, v162
	s_waitcnt lgkmcnt(0)
	v_add_f32_e32 v160, v160, v164
	v_add_f32_e32 v162, v162, v165
	ds_bpermute_b32 v164, v6, v160
	ds_bpermute_b32 v165, v6, v162
	s_waitcnt lgkmcnt(0)
	v_add_f32_e32 v160, v160, v164
	v_add_f32_e32 v162, v162, v165
	ds_bpermute_b32 v164, v7, v160
	ds_bpermute_b32 v165, v7, v162
	s_waitcnt lgkmcnt(0)
	v_add_f32_e32 v160, v160, v164
	v_add_f32_e32 v162, v162, v165
	ds_bpermute_b32 v164, v9, v160
	ds_bpermute_b32 v165, v9, v162
	s_waitcnt lgkmcnt(0)
	v_add_f32_e32 v160, v160, v164
	v_add_f32_e32 v162, v162, v165
	ds_bpermute_b32 v164, v10, v160
	ds_bpermute_b32 v165, v10, v162
	s_waitcnt lgkmcnt(0)
; __device__ __forceinline__ unsigned cvt_pk_bf16(float lo, float hi) { unsigned r; asm volatile("v_cvt_pk_bf16_f32 %0, %1, %2" : "=v"(r) : "v"(lo), "v"(hi)); return r; }
; __device__ __forceinline__ void norm_phase(const Params& P, unsigned char* ws, int layer, int which, int nrows, bool first, int lane, int wave, const float* pend_part, int pend_ns, const float* pend_gate) {
;     ...
; #pragma unroll
;         for (int r = 0; r < NR; ++r)
; #pragma unroll
;             for (int j = 0; j < 2; ++j)
; #pragma unroll
;                 for (int q = 0; q < 2; ++q) ss[r] += (v[r][j][q][0] * v[r][j][q][0] + v[r][j][q][1] * v[r][j][q][1]) + (v[r][j][q][2] * v[r][j][q][2] + v[r][j][q][3] * v[r][j][q][3]);
; #pragma unroll
;         for (int r = 0; r < NR; ++r) { const int row = row0 + r * NGW;
;             const float rstd = rsqrtf(wave_sum(ss[r], lane) * (1.0f / DM) + EPS);
;             const float* mod = (const float*)(ws + WS_MOD) + (size_t)(layer * 9 + (row >> 12)) * 6144 + which * 3 * DM;
; #pragma unroll
;             for (int j = 0; j < 2; ++j) { const int col = 8 * lane + 512 * j; u32x4 hw, xw;
; #pragma unroll
;                 for (int q = 0; q < 2; ++q) {
;                     const f32x4 g4 = *(const f32x4*)(g + col + 4 * q), sh = *(const f32x4*)(mod + col + 4 * q), sc = *(const f32x4*)(mod + DM + col + 4 * q);
;                     const f32x4 h = (v[r][j][q] * rstd) * g4 * (sc + 1.0f) + sh;
;                     if (q == 0) { hw.x = cvt_pk_bf16(h[0], h[1]); hw.y = cvt_pk_bf16(h[2], h[3]); xw.x = cvt_pk_bf16(v[r][j][q][0], v[r][j][q][1]); xw.y = cvt_pk_bf16(v[r][j][q][2], v[r][j][q][3]); }
;                     else { hw.z = cvt_pk_bf16(h[0], h[1]); hw.w = cvt_pk_bf16(h[2], h[3]); xw.z = cvt_pk_bf16(v[r][j][q][0], v[r][j][q][1]); xw.w = cvt_pk_bf16(v[r][j][q][2], v[r][j][q][3]); }
;                 }
;                 *(u32x4*)(H + (size_t)row * DM + col) = hw;
	v_add_f32_e32 v160, v160, v164
	v_add_f32_e32 v162, v162, v165
	ds_bpermute_b32 v164, v11, v160
	ds_bpermute_b32 v165, v11, v162
	s_waitcnt lgkmcnt(0)
	v_add_f32_e32 v160, v160, v164
	v_add_f32_e32 v162, v162, v165
	v_fmamk_f32 v160, v160, 0x3a800000, v194
	v_fmamk_f32 v162, v162, 0x3a800000, v194
	v_rsq_f32_e32 v160, v160
	v_rsq_f32_e32 v162, v162
	v_pk_add_f32 v[48:49], v[48:49], 1.0 op_sel_hi:[1,0]
	v_pk_add_f32 v[50:51], v[50:51], 1.0 op_sel_hi:[1,0]
	v_pk_add_f32 v[52:53], v[52:53], 1.0 op_sel_hi:[1,0]
	v_pk_add_f32 v[54:55], v[54:55], 1.0 op_sel_hi:[1,0]
	v_pk_add_f32 v[56:57], v[56:57], 1.0 op_sel_hi:[1,0]
	v_pk_add_f32 v[58:59], v[58:59], 1.0 op_sel_hi:[1,0]
	v_pk_add_f32 v[60:61], v[60:61], 1.0 op_sel_hi:[1,0]
	v_pk_add_f32 v[62:63], v[62:63], 1.0 op_sel_hi:[1,0]
	v_pk_mul_f32 v[128:129], v[160:161], v[128:129] op_sel_hi:[0,1]
	v_pk_mul_f32 v[130:131], v[160:161], v[130:131] op_sel_hi:[0,1]
	v_pk_mul_f32 v[132:133], v[160:161], v[132:133] op_sel_hi:[0,1]
	v_pk_mul_f32 v[134:135], v[160:161], v[134:135] op_sel_hi:[0,1]
	v_pk_mul_f32 v[136:137], v[160:161], v[136:137] op_sel_hi:[0,1]
	v_pk_mul_f32 v[138:139], v[160:161], v[138:139] op_sel_hi:[0,1]
	v_pk_mul_f32 v[140:141], v[160:161], v[140:141] op_sel_hi:[0,1]
	v_pk_mul_f32 v[142:143], v[160:161], v[142:143] op_sel_hi:[0,1]
	v_pk_mul_f32 v[128:129], v[16:17], v[128:129]
	v_pk_mul_f32 v[130:131], v[18:19], v[130:131]
	v_pk_mul_f32 v[132:133], v[20:21], v[132:133]
	v_pk_mul_f32 v[134:135], v[22:23], v[134:135]
	v_pk_mul_f32 v[136:137], v[24:25], v[136:137]
	v_pk_mul_f32 v[138:139], v[26:27], v[138:139]
	v_pk_mul_f32 v[140:141], v[28:29], v[140:141]
	v_pk_mul_f32 v[142:143], v[30:31], v[142:143]
	v_pk_fma_f32 v[128:129], v[48:49], v[128:129], v[32:33]
	v_pk_fma_f32 v[130:131], v[50:51], v[130:131], v[34:35]
	v_pk_fma_f32 v[132:133], v[52:53], v[132:133], v[36:37]
	v_pk_fma_f32 v[134:135], v[54:55], v[134:135], v[38:39]
	v_pk_fma_f32 v[136:137], v[56:57], v[136:137], v[40:41]
	v_pk_fma_f32 v[138:139], v[58:59], v[138:139], v[42:43]
	v_pk_fma_f32 v[140:141], v[60:61], v[140:141], v[44:45]
	v_pk_fma_f32 v[142:143], v[62:63], v[142:143], v[46:47]
	v_cvt_pk_bf16_f32 v176, v128, v129
	v_cvt_pk_bf16_f32 v177, v130, v131
	v_cvt_pk_bf16_f32 v178, v132, v133
	v_cvt_pk_bf16_f32 v179, v134, v135
	v_cvt_pk_bf16_f32 v180, v136, v137
	v_cvt_pk_bf16_f32 v181, v138, v139
	v_cvt_pk_bf16_f32 v182, v140, v141
	v_cvt_pk_bf16_f32 v183, v142, v143
	s_add_i32 s10, s98, 0x2
	s_lshl_b32 s10, s10, 11
	s_add_u32 s28, s26, s10
	s_addc_u32 s29, s27, 0
	global_store_dwordx4 v2, v[176:179], s[28:29] sc1
	global_store_dwordx4 v2, v[180:183], s[28:29] offset:1024 sc1
	v_pk_mul_f32 v[144:145], v[162:163], v[144:145] op_sel_hi:[0,1]
	v_pk_mul_f32 v[146:147], v[162:163], v[146:147] op_sel_hi:[0,1]
	v_pk_mul_f32 v[148:149], v[162:163], v[148:149] op_sel_hi:[0,1]
	v_pk_mul_f32 v[150:151], v[162:163], v[150:151] op_sel_hi:[0,1]
	v_pk_mul_f32 v[152:153], v[162:163], v[152:153] op_sel_hi:[0,1]
	v_pk_mul_f32 v[154:155], v[162:163], v[154:155] op_sel_hi:[0,1]
	v_pk_mul_f32 v[156:157], v[162:163], v[156:157] op_sel_hi:[0,1]
	v_pk_mul_f32 v[158:159], v[162:163], v[158:159] op_sel_hi:[0,1]
	v_pk_mul_f32 v[144:145], v[16:17], v[144:145]
	v_pk_mul_f32 v[146:147], v[18:19], v[146:147]
	v_pk_mul_f32 v[148:149], v[20:21], v[148:149]
	v_pk_mul_f32 v[150:151], v[22:23], v[150:151]
	v_pk_mul_f32 v[152:153], v[24:25], v[152:153]
	v_pk_mul_f32 v[154:155], v[26:27], v[154:155]
	v_pk_mul_f32 v[156:157], v[28:29], v[156:157]
	v_pk_mul_f32 v[158:159], v[30:31], v[158:159]
	v_pk_fma_f32 v[144:145], v[48:49], v[144:145], v[32:33]
	v_pk_fma_f32 v[146:147], v[50:51], v[146:147], v[34:35]
	v_pk_fma_f32 v[148:149], v[52:53], v[148:149], v[36:37]
	v_pk_fma_f32 v[150:151], v[54:55], v[150:151], v[38:39]
	v_pk_fma_f32 v[152:153], v[56:57], v[152:153], v[40:41]
	v_pk_fma_f32 v[154:155], v[58:59], v[154:155], v[42:43]
	v_pk_fma_f32 v[156:157], v[60:61], v[156:157], v[44:45]
	v_pk_fma_f32 v[158:159], v[62:63], v[158:159], v[46:47]
	v_cvt_pk_bf16_f32 v184, v144, v145
	v_cvt_pk_bf16_f32 v185, v146, v147
	v_cvt_pk_bf16_f32 v186, v148, v149
	v_cvt_pk_bf16_f32 v187, v150, v151
	v_cvt_pk_bf16_f32 v188, v152, v153
	v_cvt_pk_bf16_f32 v189, v154, v155
	v_cvt_pk_bf16_f32 v190, v156, v157
	v_cvt_pk_bf16_f32 v191, v158, v159
	s_add_i32 s10, s98, 0x3
	s_lshl_b32 s10, s10, 11
	s_add_u32 s28, s26, s10
	s_addc_u32 s29, s27, 0
	global_store_dwordx4 v2, v[184:187], s[28:29] sc1
	global_store_dwordx4 v2, v[188:191], s[28:29] offset:1024 sc1
	s_add_i32 s10, s98, 0xa
	s_lshl_b32 s10, s10, 11
	s_add_u32 s28, s22, s10
	s_addc_u32 s29, s23, 0
	global_load_dwordx4 v[80:83], v2, s[28:29]
	global_load_dwordx4 v[84:87], v2, s[28:29] offset:1024
	s_add_i32 s10, s98, 0xb
	s_lshl_b32 s10, s10, 11
	s_add_u32 s28, s22, s10
	s_addc_u32 s29, s23, 0
	global_load_dwordx4 v[88:91], v2, s[28:29]
	global_load_dwordx4 v[92:95], v2, s[28:29] offset:1024
	s_waitcnt vmcnt(20)
; __device__ __forceinline__ unsigned cvt_pk_bf16(float lo, float hi) { unsigned r; asm volatile("v_cvt_pk_bf16_f32 %0, %1, %2" : "=v"(r) : "v"(lo), "v"(hi)); return r; }
; __device__ __forceinline__ void norm_phase(const Params& P, unsigned char* ws, int layer, int which, int nrows, bool first, int lane, int wave, const float* pend_part, int pend_ns, const float* pend_gate) {
;     ...
; #pragma unroll
;         for (int r = 0; r < NR; ++r)
; #pragma unroll
;             for (int j = 0; j < 2; ++j)
; #pragma unroll
;                 for (int q = 0; q < 2; ++q) ss[r] += (v[r][j][q][0] * v[r][j][q][0] + v[r][j][q][1] * v[r][j][q][1]) + (v[r][j][q][2] * v[r][j][q][2] + v[r][j][q][3] * v[r][j][q][3]);
; #pragma unroll
;         for (int r = 0; r < NR; ++r) { const int row = row0 + r * NGW;
;             const float rstd = rsqrtf(wave_sum(ss[r], lane) * (1.0f / DM) + EPS);
;             const float* mod = (const float*)(ws + WS_MOD) + (size_t)(layer * 9 + (row >> 12)) * 6144 + which * 3 * DM;
; #pragma unroll
;             for (int j = 0; j < 2; ++j) { const int col = 8 * lane + 512 * j; u32x4 hw, xw;
; #pragma unroll
;                 for (int q = 0; q < 2; ++q) {
;                     const f32x4 g4 = *(const f32x4*)(g + col + 4 * q), sh = *(const f32x4*)(mod + col + 4 * q), sc = *(const f32x4*)(mod + DM + col + 4 * q);
;                     const f32x4 h = (v[r][j][q] * rstd) * g4 * (sc + 1.0f) + sh;
;                     if (q == 0) { hw.x = cvt_pk_bf16(h[0], h[1]); hw.y = cvt_pk_bf16(h[2], h[3]); xw.x = cvt_pk_bf16(v[r][j][q][0], v[r][j][q][1]); xw.y = cvt_pk_bf16(v[r][j][q][2], v[r][j][q][3]); }
;                     else { hw.z = cvt_pk_bf16(h[0], h[1]); hw.w = cvt_pk_bf16(h[2], h[3]); xw.z = cvt_pk_bf16(v[r][j][q][0], v[r][j][q][1]); xw.w = cvt_pk_bf16(v[r][j][q][2], v[r][j][q][3]); }
;                 }
;                 *(u32x4*)(H + (size_t)row * DM + col) = hw;
	ds_read_b128 v[32:35], v15 offset:0
	ds_read_b128 v[36:39], v15 offset:16
	ds_read_b128 v[40:43], v15 offset:2048
	ds_read_b128 v[44:47], v15 offset:2064
	ds_read_b128 v[48:51], v15 offset:32768
	ds_read_b128 v[52:55], v15 offset:32784
	ds_read_b128 v[56:59], v15 offset:34816
	ds_read_b128 v[60:63], v15 offset:34832
	v_lshlrev_b32_e32 v128, 16, v96
	v_and_b32_e32 v129, 0xffff0000, v96
	v_lshlrev_b32_e32 v130, 16, v97
	v_and_b32_e32 v131, 0xffff0000, v97
	v_lshlrev_b32_e32 v132, 16, v98
	v_and_b32_e32 v133, 0xffff0000, v98
	v_lshlrev_b32_e32 v134, 16, v99
	v_and_b32_e32 v135, 0xffff0000, v99
	v_lshlrev_b32_e32 v136, 16, v100
	v_and_b32_e32 v137, 0xffff0000, v100
	v_lshlrev_b32_e32 v138, 16, v101
	v_and_b32_e32 v139, 0xffff0000, v101
	v_lshlrev_b32_e32 v140, 16, v102
	v_and_b32_e32 v141, 0xffff0000, v102
	v_lshlrev_b32_e32 v142, 16, v103
	v_and_b32_e32 v143, 0xffff0000, v103
	v_lshlrev_b32_e32 v144, 16, v104
	v_and_b32_e32 v145, 0xffff0000, v104
	v_lshlrev_b32_e32 v146, 16, v105
	v_and_b32_e32 v147, 0xffff0000, v105
	v_lshlrev_b32_e32 v148, 16, v106
	v_and_b32_e32 v149, 0xffff0000, v106
	v_lshlrev_b32_e32 v150, 16, v107
	v_and_b32_e32 v151, 0xffff0000, v107
	v_lshlrev_b32_e32 v152, 16, v108
	v_and_b32_e32 v153, 0xffff0000, v108
	v_lshlrev_b32_e32 v154, 16, v109
	v_and_b32_e32 v155, 0xffff0000, v109
	v_lshlrev_b32_e32 v156, 16, v110
	v_and_b32_e32 v157, 0xffff0000, v110
	v_lshlrev_b32_e32 v158, 16, v111
	v_and_b32_e32 v159, 0xffff0000, v111
	v_pk_mul_f32 v[160:161], v[128:129], v[128:129]
	v_pk_mul_f32 v[162:163], v[144:145], v[144:145]
	v_pk_fma_f32 v[160:161], v[130:131], v[130:131], v[160:161]
	v_pk_fma_f32 v[162:163], v[146:147], v[146:147], v[162:163]
	v_pk_fma_f32 v[160:161], v[132:133], v[132:133], v[160:161]
	v_pk_fma_f32 v[162:163], v[148:149], v[148:149], v[162:163]
	v_pk_fma_f32 v[160:161], v[134:135], v[134:135], v[160:161]
	v_pk_fma_f32 v[162:163], v[150:151], v[150:151], v[162:163]
	v_pk_fma_f32 v[160:161], v[136:137], v[136:137], v[160:161]
	v_pk_fma_f32 v[162:163], v[152:153], v[152:153], v[162:163]
	v_pk_fma_f32 v[160:161], v[138:139], v[138:139], v[160:161]
	v_pk_fma_f32 v[162:163], v[154:155], v[154:155], v[162:163]
	v_pk_fma_f32 v[160:161], v[140:141], v[140:141], v[160:161]
	v_pk_fma_f32 v[162:163], v[156:157], v[156:157], v[162:163]
	v_pk_fma_f32 v[160:161], v[142:143], v[142:143], v[160:161]
	v_pk_fma_f32 v[162:163], v[158:159], v[158:159], v[162:163]
	v_add_f32_e32 v160, v160, v161
	v_add_f32_e32 v162, v162, v163
	ds_bpermute_b32 v164, v5, v160
	ds_bpermute_b32 v165, v5, v162
	s_waitcnt lgkmcnt(0)
	v_add_f32_e32 v160, v160, v164
	v_add_f32_e32 v162, v162, v165
	ds_bpermute_b32 v164, v6, v160
	ds_bpermute_b32 v165, v6, v162
	s_waitcnt lgkmcnt(0)
	v_add_f32_e32 v160, v160, v164
	v_add_f32_e32 v162, v162, v165
	ds_bpermute_b32 v164, v7, v160
	ds_bpermute_b32 v165, v7, v162
	s_waitcnt lgkmcnt(0)
	v_add_f32_e32 v160, v160, v164
	v_add_f32_e32 v162, v162, v165
	ds_bpermute_b32 v164, v9, v160
	ds_bpermute_b32 v165, v9, v162
	s_waitcnt lgkmcnt(0)
	v_add_f32_e32 v160, v160, v164
	v_add_f32_e32 v162, v162, v165
	ds_bpermute_b32 v164, v10, v160
	ds_bpermute_b32 v165, v10, v162
	s_waitcnt lgkmcnt(0)
	v_add_f32_e32 v160, v160, v164
	v_add_f32_e32 v162, v162, v165
	ds_bpermute_b32 v164, v11, v160
	ds_bpermute_b32 v165, v11, v162
	s_waitcnt lgkmcnt(0)
	v_add_f32_e32 v160, v160, v164
	v_add_f32_e32 v162, v162, v165
	v_fmamk_f32 v160, v160, 0x3a800000, v194
	v_fmamk_f32 v162, v162, 0x3a800000, v194
	v_rsq_f32_e32 v160, v160
	v_rsq_f32_e32 v162, v162
	v_pk_add_f32 v[48:49], v[48:49], 1.0 op_sel_hi:[1,0]
	v_pk_add_f32 v[50:51], v[50:51], 1.0 op_sel_hi:[1,0]
	v_pk_add_f32 v[52:53], v[52:53], 1.0 op_sel_hi:[1,0]
	v_pk_add_f32 v[54:55], v[54:55], 1.0 op_sel_hi:[1,0]
	v_pk_add_f32 v[56:57], v[56:57], 1.0 op_sel_hi:[1,0]
	v_pk_add_f32 v[58:59], v[58:59], 1.0 op_sel_hi:[1,0]
	v_pk_add_f32 v[60:61], v[60:61], 1.0 op_sel_hi:[1,0]
	v_pk_add_f32 v[62:63], v[62:63], 1.0 op_sel_hi:[1,0]
	v_pk_mul_f32 v[128:129], v[160:161], v[128:129] op_sel_hi:[0,1]
	v_pk_mul_f32 v[130:131], v[160:161], v[130:131] op_sel_hi:[0,1]
	v_pk_mul_f32 v[132:133], v[160:161], v[132:133] op_sel_hi:[0,1]
	v_pk_mul_f32 v[134:135], v[160:161], v[134:135] op_sel_hi:[0,1]
	v_pk_mul_f32 v[136:137], v[160:161], v[136:137] op_sel_hi:[0,1]
	v_pk_mul_f32 v[138:139], v[160:161], v[138:139] op_sel_hi:[0,1]
	v_pk_mul_f32 v[140:141], v[160:161], v[140:141] op_sel_hi:[0,1]
	v_pk_mul_f32 v[142:143], v[160:161], v[142:143] op_sel_hi:[0,1]
	v_pk_mul_f32 v[128:129], v[16:17], v[128:129]
	v_pk_mul_f32 v[130:131], v[18:19], v[130:131]
	v_pk_mul_f32 v[132:133], v[20:21], v[132:133]
	v_pk_mul_f32 v[134:135], v[22:23], v[134:135]
	v_pk_mul_f32 v[136:137], v[24:25], v[136:137]
	v_pk_mul_f32 v[138:139], v[26:27], v[138:139]
	v_pk_mul_f32 v[140:141], v[28:29], v[140:141]
	v_pk_mul_f32 v[142:143], v[30:31], v[142:143]
	v_pk_fma_f32 v[128:129], v[48:49], v[128:129], v[32:33]
	v_pk_fma_f32 v[130:131], v[50:51], v[130:131], v[34:35]
	v_pk_fma_f32 v[132:133], v[52:53], v[132:133], v[36:37]
	v_pk_fma_f32 v[134:135], v[54:55], v[134:135], v[38:39]
	v_pk_fma_f32 v[136:137], v[56:57], v[136:137], v[40:41]
	v_pk_fma_f32 v[138:139], v[58:59], v[138:139], v[42:43]
	v_pk_fma_f32 v[140:141], v[60:61], v[140:141], v[44:45]
	v_pk_fma_f32 v[142:143], v[62:63], v[142:143], v[46:47]
	v_cvt_pk_bf16_f32 v176, v128, v129
	v_cvt_pk_bf16_f32 v177, v130, v131
	v_cvt_pk_bf16_f32 v178, v132, v133
	v_cvt_pk_bf16_f32 v179, v134, v135
	v_cvt_pk_bf16_f32 v180, v136, v137
	v_cvt_pk_bf16_f32 v181, v138, v139
	v_cvt_pk_bf16_f32 v182, v140, v141
	v_cvt_pk_bf16_f32 v183, v142, v143
	s_add_i32 s10, s98, 0x4
	s_lshl_b32 s10, s10, 11
; __device__ __forceinline__ void norm_phase(const Params& P, unsigned char* ws, int layer, int which, int nrows, bool first, int lane, int wave, const float* pend_part, int pend_ns, const float* pend_gate) {
;     ...
;         for (int r = 0; r < NR; ++r) { const int row = row0 + r * NGW; ss[r] = 0.f;
; #pragma unroll
;             for (int j = 0; j < 2; ++j) { const int col = 8 * lane + 512 * j;
;                 if (first) { v[r][j][0] = *(const f32x4*)(P.in[I_X] + (size_t)row * DM + col); v[r][j][1] = *(const f32x4*)(P.in[I_X] + (size_t)row * DM + col + 4); }
;                 else { const u32x4 w = *(const u32x4*)(XB + (size_t)row * DM + col); v[r][j][0] = bf4_to_f32((u32x2){w.x, w.y}); v[r][j][1] = bf4_to_f32((u32x2){w.z, w.w}); } } }
; #pragma unroll
;         for (int r = 0; r < NR; ++r)
; #pragma unroll
;             for (int j = 0; j < 2; ++j)
; #pragma unroll
;                 for (int q = 0; q < 2; ++q) ss[r] += (v[r][j][q][0] * v[r][j][q][0] + v[r][j][q][1] * v[r][j][q][1]) + (v[r][j][q][2] * v[r][j][q][2] + v[r][j][q][3] * v[r][j][q][3]);
; #pragma unroll
;         for (int r = 0; r < NR; ++r) { const int row = row0 + r * NGW;
;             const float rstd = rsqrtf(wave_sum(ss[r], lane) * (1.0f / DM) + EPS);
;             const float* mod = (const float*)(ws + WS_MOD) + (size_t)(layer * 9 + (row >> 12)) * 6144 + which * 3 * DM;
; #pragma unroll
;             for (int j = 0; j < 2; ++j) { const int col = 8 * lane + 512 * j; u32x4 hw, xw;
; #pragma unroll
;                 for (int q = 0; q < 2; ++q) {
;                     const f32x4 g4 = *(const f32x4*)(g + col + 4 * q), sh = *(const f32x4*)(mod + col + 4 * q), sc = *(const f32x4*)(mod + DM + col + 4 * q);
;                     const f32x4 h = (v[r][j][q] * rstd) * g4 * (sc + 1.0f) + sh;
;                     if (q == 0) { hw.x = cvt_pk_bf16(h[0], h[1]); hw.y = cvt_pk_bf16(h[2], h[3]); xw.x = cvt_pk_bf16(v[r][j][q][0], v[r][j][q][1]); xw.y = cvt_pk_bf16(v[r][j][q][2], v[r][j][q][3]); }
;                     else { hw.z = cvt_pk_bf16(h[0], h[1]); hw.w = cvt_pk_bf16(h[2], h[3]); xw.z = cvt_pk_bf16(v[r][j][q][0], v[r][j][q][1]); xw.w = cvt_pk_bf16(v[r][j][q][2], v[r][j][q][3]); }
;                 }
;                 *(u32x4*)(H + (size_t)row * DM + col) = hw;
	s_add_u32 s28, s26, s10
	s_addc_u32 s29, s27, 0
	global_store_dwordx4 v2, v[176:179], s[28:29] sc1
	global_store_dwordx4 v2, v[180:183], s[28:29] offset:1024 sc1
	v_pk_mul_f32 v[144:145], v[162:163], v[144:145] op_sel_hi:[0,1]
	v_pk_mul_f32 v[146:147], v[162:163], v[146:147] op_sel_hi:[0,1]
	v_pk_mul_f32 v[148:149], v[162:163], v[148:149] op_sel_hi:[0,1]
	v_pk_mul_f32 v[150:151], v[162:163], v[150:151] op_sel_hi:[0,1]
	v_pk_mul_f32 v[152:153], v[162:163], v[152:153] op_sel_hi:[0,1]
	v_pk_mul_f32 v[154:155], v[162:163], v[154:155] op_sel_hi:[0,1]
	v_pk_mul_f32 v[156:157], v[162:163], v[156:157] op_sel_hi:[0,1]
	v_pk_mul_f32 v[158:159], v[162:163], v[158:159] op_sel_hi:[0,1]
	v_pk_mul_f32 v[144:145], v[16:17], v[144:145]
	v_pk_mul_f32 v[146:147], v[18:19], v[146:147]
	v_pk_mul_f32 v[148:149], v[20:21], v[148:149]
	v_pk_mul_f32 v[150:151], v[22:23], v[150:151]
	v_pk_mul_f32 v[152:153], v[24:25], v[152:153]
	v_pk_mul_f32 v[154:155], v[26:27], v[154:155]
	v_pk_mul_f32 v[156:157], v[28:29], v[156:157]
	v_pk_mul_f32 v[158:159], v[30:31], v[158:159]
	v_pk_fma_f32 v[144:145], v[48:49], v[144:145], v[32:33]
	v_pk_fma_f32 v[146:147], v[50:51], v[146:147], v[34:35]
	v_pk_fma_f32 v[148:149], v[52:53], v[148:149], v[36:37]
	v_pk_fma_f32 v[150:151], v[54:55], v[150:151], v[38:39]
	v_pk_fma_f32 v[152:153], v[56:57], v[152:153], v[40:41]
	v_pk_fma_f32 v[154:155], v[58:59], v[154:155], v[42:43]
	v_pk_fma_f32 v[156:157], v[60:61], v[156:157], v[44:45]
	v_pk_fma_f32 v[158:159], v[62:63], v[158:159], v[46:47]
	v_cvt_pk_bf16_f32 v184, v144, v145
	v_cvt_pk_bf16_f32 v185, v146, v147
	v_cvt_pk_bf16_f32 v186, v148, v149
	v_cvt_pk_bf16_f32 v187, v150, v151
	v_cvt_pk_bf16_f32 v188, v152, v153
	v_cvt_pk_bf16_f32 v189, v154, v155
	v_cvt_pk_bf16_f32 v190, v156, v157
	v_cvt_pk_bf16_f32 v191, v158, v159
	s_add_i32 s10, s98, 0x5
	s_lshl_b32 s10, s10, 11
	s_add_u32 s28, s26, s10
	s_addc_u32 s29, s27, 0
	global_store_dwordx4 v2, v[184:187], s[28:29] sc1
	global_store_dwordx4 v2, v[188:191], s[28:29] offset:1024 sc1
	s_add_i32 s10, s98, 0xc
	s_lshl_b32 s10, s10, 11
	s_add_u32 s28, s22, s10
	s_addc_u32 s29, s23, 0
	global_load_dwordx4 v[96:99], v2, s[28:29]
	global_load_dwordx4 v[100:103], v2, s[28:29] offset:1024
	s_add_i32 s10, s98, 0xd
	s_lshl_b32 s10, s10, 11
	s_add_u32 s28, s22, s10
	s_addc_u32 s29, s23, 0
	global_load_dwordx4 v[104:107], v2, s[28:29]
	global_load_dwordx4 v[108:111], v2, s[28:29] offset:1024
	s_waitcnt vmcnt(24)
	ds_read_b128 v[32:35], v15 offset:0
	ds_read_b128 v[36:39], v15 offset:16
	ds_read_b128 v[40:43], v15 offset:2048
	ds_read_b128 v[44:47], v15 offset:2064
	ds_read_b128 v[48:51], v15 offset:32768
	ds_read_b128 v[52:55], v15 offset:32784
	ds_read_b128 v[56:59], v15 offset:34816
	ds_read_b128 v[60:63], v15 offset:34832
	v_lshlrev_b32_e32 v128, 16, v112
	v_and_b32_e32 v129, 0xffff0000, v112
	v_lshlrev_b32_e32 v130, 16, v113
	v_and_b32_e32 v131, 0xffff0000, v113
	v_lshlrev_b32_e32 v132, 16, v114
	v_and_b32_e32 v133, 0xffff0000, v114
	v_lshlrev_b32_e32 v134, 16, v115
	v_and_b32_e32 v135, 0xffff0000, v115
	v_lshlrev_b32_e32 v136, 16, v116
	v_and_b32_e32 v137, 0xffff0000, v116
	v_lshlrev_b32_e32 v138, 16, v117
	v_and_b32_e32 v139, 0xffff0000, v117
	v_lshlrev_b32_e32 v140, 16, v118
	v_and_b32_e32 v141, 0xffff0000, v118
	v_lshlrev_b32_e32 v142, 16, v119
	v_and_b32_e32 v143, 0xffff0000, v119
	v_lshlrev_b32_e32 v144, 16, v120
	v_and_b32_e32 v145, 0xffff0000, v120
	v_lshlrev_b32_e32 v146, 16, v121
	v_and_b32_e32 v147, 0xffff0000, v121
	v_lshlrev_b32_e32 v148, 16, v122
	v_and_b32_e32 v149, 0xffff0000, v122
	v_lshlrev_b32_e32 v150, 16, v123
	v_and_b32_e32 v151, 0xffff0000, v123
	v_lshlrev_b32_e32 v152, 16, v124
	v_and_b32_e32 v153, 0xffff0000, v124
	v_lshlrev_b32_e32 v154, 16, v125
	v_and_b32_e32 v155, 0xffff0000, v125
	v_lshlrev_b32_e32 v156, 16, v126
	v_and_b32_e32 v157, 0xffff0000, v126
	v_lshlrev_b32_e32 v158, 16, v127
	v_and_b32_e32 v159, 0xffff0000, v127
	v_pk_mul_f32 v[160:161], v[128:129], v[128:129]
	v_pk_mul_f32 v[162:163], v[144:145], v[144:145]
	v_pk_fma_f32 v[160:161], v[130:131], v[130:131], v[160:161]
	v_pk_fma_f32 v[162:163], v[146:147], v[146:147], v[162:163]
	v_pk_fma_f32 v[160:161], v[132:133], v[132:133], v[160:161]
	v_pk_fma_f32 v[162:163], v[148:149], v[148:149], v[162:163]
	v_pk_fma_f32 v[160:161], v[134:135], v[134:135], v[160:161]
	v_pk_fma_f32 v[162:163], v[150:151], v[150:151], v[162:163]
	v_pk_fma_f32 v[160:161], v[136:137], v[136:137], v[160:161]
	v_pk_fma_f32 v[162:163], v[152:153], v[152:153], v[162:163]
	v_pk_fma_f32 v[160:161], v[138:139], v[138:139], v[160:161]
	v_pk_fma_f32 v[162:163], v[154:155], v[154:155], v[162:163]
	v_pk_fma_f32 v[160:161], v[140:141], v[140:141], v[160:161]
	v_pk_fma_f32 v[162:163], v[156:157], v[156:157], v[162:163]
	v_pk_fma_f32 v[160:161], v[142:143], v[142:143], v[160:161]
	v_pk_fma_f32 v[162:163], v[158:159], v[158:159], v[162:163]
	v_add_f32_e32 v160, v160, v161
	v_add_f32_e32 v162, v162, v163
	ds_bpermute_b32 v164, v5, v160
	ds_bpermute_b32 v165, v5, v162
	s_waitcnt lgkmcnt(0)
	v_add_f32_e32 v160, v160, v164
	v_add_f32_e32 v162, v162, v165
	ds_bpermute_b32 v164, v6, v160
	ds_bpermute_b32 v165, v6, v162
	s_waitcnt lgkmcnt(0)
	v_add_f32_e32 v160, v160, v164
	v_add_f32_e32 v162, v162, v165
	ds_bpermute_b32 v164, v7, v160
	ds_bpermute_b32 v165, v7, v162
	s_waitcnt lgkmcnt(0)
	v_add_f32_e32 v160, v160, v164
	v_add_f32_e32 v162, v162, v165
	ds_bpermute_b32 v164, v9, v160
	ds_bpermute_b32 v165, v9, v162
	s_waitcnt lgkmcnt(0)
	v_add_f32_e32 v160, v160, v164
	v_add_f32_e32 v162, v162, v165
	ds_bpermute_b32 v164, v10, v160
	ds_bpermute_b32 v165, v10, v162
	s_waitcnt lgkmcnt(0)
; __device__ __forceinline__ unsigned cvt_pk_bf16(float lo, float hi) { unsigned r; asm volatile("v_cvt_pk_bf16_f32 %0, %1, %2" : "=v"(r) : "v"(lo), "v"(hi)); return r; }
; __device__ __forceinline__ void norm_phase(const Params& P, unsigned char* ws, int layer, int which, int nrows, bool first, int lane, int wave, const float* pend_part, int pend_ns, const float* pend_gate) {
;     ...
; #pragma unroll
;         for (int r = 0; r < NR; ++r)
; #pragma unroll
;             for (int j = 0; j < 2; ++j)
; #pragma unroll
;                 for (int q = 0; q < 2; ++q) ss[r] += (v[r][j][q][0] * v[r][j][q][0] + v[r][j][q][1] * v[r][j][q][1]) + (v[r][j][q][2] * v[r][j][q][2] + v[r][j][q][3] * v[r][j][q][3]);
; #pragma unroll
;         for (int r = 0; r < NR; ++r) { const int row = row0 + r * NGW;
;             const float rstd = rsqrtf(wave_sum(ss[r], lane) * (1.0f / DM) + EPS);
;             const float* mod = (const float*)(ws + WS_MOD) + (size_t)(layer * 9 + (row >> 12)) * 6144 + which * 3 * DM;
; #pragma unroll
;             for (int j = 0; j < 2; ++j) { const int col = 8 * lane + 512 * j; u32x4 hw, xw;
; #pragma unroll
;                 for (int q = 0; q < 2; ++q) {
;                     const f32x4 g4 = *(const f32x4*)(g + col + 4 * q), sh = *(const f32x4*)(mod + col + 4 * q), sc = *(const f32x4*)(mod + DM + col + 4 * q);
;                     const f32x4 h = (v[r][j][q] * rstd) * g4 * (sc + 1.0f) + sh;
;                     if (q == 0) { hw.x = cvt_pk_bf16(h[0], h[1]); hw.y = cvt_pk_bf16(h[2], h[3]); xw.x = cvt_pk_bf16(v[r][j][q][0], v[r][j][q][1]); xw.y = cvt_pk_bf16(v[r][j][q][2], v[r][j][q][3]); }
;                     else { hw.z = cvt_pk_bf16(h[0], h[1]); hw.w = cvt_pk_bf16(h[2], h[3]); xw.z = cvt_pk_bf16(v[r][j][q][0], v[r][j][q][1]); xw.w = cvt_pk_bf16(v[r][j][q][2], v[r][j][q][3]); }
;                 }
;                 *(u32x4*)(H + (size_t)row * DM + col) = hw;
	v_add_f32_e32 v160, v160, v164
	v_add_f32_e32 v162, v162, v165
	ds_bpermute_b32 v164, v11, v160
	ds_bpermute_b32 v165, v11, v162
	s_waitcnt lgkmcnt(0)
	v_add_f32_e32 v160, v160, v164
	v_add_f32_e32 v162, v162, v165
	v_fmamk_f32 v160, v160, 0x3a800000, v194
	v_fmamk_f32 v162, v162, 0x3a800000, v194
	v_rsq_f32_e32 v160, v160
	v_rsq_f32_e32 v162, v162
	v_pk_add_f32 v[48:49], v[48:49], 1.0 op_sel_hi:[1,0]
	v_pk_add_f32 v[50:51], v[50:51], 1.0 op_sel_hi:[1,0]
	v_pk_add_f32 v[52:53], v[52:53], 1.0 op_sel_hi:[1,0]
	v_pk_add_f32 v[54:55], v[54:55], 1.0 op_sel_hi:[1,0]
	v_pk_add_f32 v[56:57], v[56:57], 1.0 op_sel_hi:[1,0]
	v_pk_add_f32 v[58:59], v[58:59], 1.0 op_sel_hi:[1,0]
	v_pk_add_f32 v[60:61], v[60:61], 1.0 op_sel_hi:[1,0]
	v_pk_add_f32 v[62:63], v[62:63], 1.0 op_sel_hi:[1,0]
	v_pk_mul_f32 v[128:129], v[160:161], v[128:129] op_sel_hi:[0,1]
	v_pk_mul_f32 v[130:131], v[160:161], v[130:131] op_sel_hi:[0,1]
	v_pk_mul_f32 v[132:133], v[160:161], v[132:133] op_sel_hi:[0,1]
	v_pk_mul_f32 v[134:135], v[160:161], v[134:135] op_sel_hi:[0,1]
	v_pk_mul_f32 v[136:137], v[160:161], v[136:137] op_sel_hi:[0,1]
	v_pk_mul_f32 v[138:139], v[160:161], v[138:139] op_sel_hi:[0,1]
	v_pk_mul_f32 v[140:141], v[160:161], v[140:141] op_sel_hi:[0,1]
	v_pk_mul_f32 v[142:143], v[160:161], v[142:143] op_sel_hi:[0,1]
	v_pk_mul_f32 v[128:129], v[16:17], v[128:129]
	v_pk_mul_f32 v[130:131], v[18:19], v[130:131]
	v_pk_mul_f32 v[132:133], v[20:21], v[132:133]
	v_pk_mul_f32 v[134:135], v[22:23], v[134:135]
	v_pk_mul_f32 v[136:137], v[24:25], v[136:137]
	v_pk_mul_f32 v[138:139], v[26:27], v[138:139]
	v_pk_mul_f32 v[140:141], v[28:29], v[140:141]
	v_pk_mul_f32 v[142:143], v[30:31], v[142:143]
	v_pk_fma_f32 v[128:129], v[48:49], v[128:129], v[32:33]
	v_pk_fma_f32 v[130:131], v[50:51], v[130:131], v[34:35]
	v_pk_fma_f32 v[132:133], v[52:53], v[132:133], v[36:37]
	v_pk_fma_f32 v[134:135], v[54:55], v[134:135], v[38:39]
	v_pk_fma_f32 v[136:137], v[56:57], v[136:137], v[40:41]
	v_pk_fma_f32 v[138:139], v[58:59], v[138:139], v[42:43]
	v_pk_fma_f32 v[140:141], v[60:61], v[140:141], v[44:45]
	v_pk_fma_f32 v[142:143], v[62:63], v[142:143], v[46:47]
	v_cvt_pk_bf16_f32 v176, v128, v129
	v_cvt_pk_bf16_f32 v177, v130, v131
	v_cvt_pk_bf16_f32 v178, v132, v133
	v_cvt_pk_bf16_f32 v179, v134, v135
	v_cvt_pk_bf16_f32 v180, v136, v137
	v_cvt_pk_bf16_f32 v181, v138, v139
	v_cvt_pk_bf16_f32 v182, v140, v141
	v_cvt_pk_bf16_f32 v183, v142, v143
	s_add_i32 s10, s98, 0x6
	s_lshl_b32 s10, s10, 11
	s_add_u32 s28, s26, s10
	s_addc_u32 s29, s27, 0
	global_store_dwordx4 v2, v[176:179], s[28:29] sc1
	global_store_dwordx4 v2, v[180:183], s[28:29] offset:1024 sc1
	v_pk_mul_f32 v[144:145], v[162:163], v[144:145] op_sel_hi:[0,1]
	v_pk_mul_f32 v[146:147], v[162:163], v[146:147] op_sel_hi:[0,1]
	v_pk_mul_f32 v[148:149], v[162:163], v[148:149] op_sel_hi:[0,1]
	v_pk_mul_f32 v[150:151], v[162:163], v[150:151] op_sel_hi:[0,1]
	v_pk_mul_f32 v[152:153], v[162:163], v[152:153] op_sel_hi:[0,1]
	v_pk_mul_f32 v[154:155], v[162:163], v[154:155] op_sel_hi:[0,1]
	v_pk_mul_f32 v[156:157], v[162:163], v[156:157] op_sel_hi:[0,1]
	v_pk_mul_f32 v[158:159], v[162:163], v[158:159] op_sel_hi:[0,1]
	v_pk_mul_f32 v[144:145], v[16:17], v[144:145]
	v_pk_mul_f32 v[146:147], v[18:19], v[146:147]
	v_pk_mul_f32 v[148:149], v[20:21], v[148:149]
	v_pk_mul_f32 v[150:151], v[22:23], v[150:151]
	v_pk_mul_f32 v[152:153], v[24:25], v[152:153]
	v_pk_mul_f32 v[154:155], v[26:27], v[154:155]
	v_pk_mul_f32 v[156:157], v[28:29], v[156:157]
	v_pk_mul_f32 v[158:159], v[30:31], v[158:159]
	v_pk_fma_f32 v[144:145], v[48:49], v[144:145], v[32:33]
	v_pk_fma_f32 v[146:147], v[50:51], v[146:147], v[34:35]
	v_pk_fma_f32 v[148:149], v[52:53], v[148:149], v[36:37]
	v_pk_fma_f32 v[150:151], v[54:55], v[150:151], v[38:39]
	v_pk_fma_f32 v[152:153], v[56:57], v[152:153], v[40:41]
	v_pk_fma_f32 v[154:155], v[58:59], v[154:155], v[42:43]
	v_pk_fma_f32 v[156:157], v[60:61], v[156:157], v[44:45]
	v_pk_fma_f32 v[158:159], v[62:63], v[158:159], v[46:47]
	v_cvt_pk_bf16_f32 v184, v144, v145
	v_cvt_pk_bf16_f32 v185, v146, v147
	v_cvt_pk_bf16_f32 v186, v148, v149
	v_cvt_pk_bf16_f32 v187, v150, v151
	v_cvt_pk_bf16_f32 v188, v152, v153
	v_cvt_pk_bf16_f32 v189, v154, v155
	v_cvt_pk_bf16_f32 v190, v156, v157
	v_cvt_pk_bf16_f32 v191, v158, v159
	s_add_i32 s10, s98, 0x7
	s_lshl_b32 s10, s10, 11
	s_add_u32 s28, s26, s10
	s_addc_u32 s29, s27, 0
	global_store_dwordx4 v2, v[184:187], s[28:29] sc1
	global_store_dwordx4 v2, v[188:191], s[28:29] offset:1024 sc1
	s_add_i32 s10, s98, 0xe
	s_lshl_b32 s10, s10, 11
	s_add_u32 s28, s22, s10
	s_addc_u32 s29, s23, 0
	global_load_dwordx4 v[112:115], v2, s[28:29]
	global_load_dwordx4 v[116:119], v2, s[28:29] offset:1024
	s_add_i32 s10, s98, 0xf
	s_lshl_b32 s10, s10, 11
	s_add_u32 s28, s22, s10
	s_addc_u32 s29, s23, 0
	global_load_dwordx4 v[120:123], v2, s[28:29]
	global_load_dwordx4 v[124:127], v2, s[28:29] offset:1024
	s_waitcnt vmcnt(24)
; __device__ __forceinline__ unsigned cvt_pk_bf16(float lo, float hi) { unsigned r; asm volatile("v_cvt_pk_bf16_f32 %0, %1, %2" : "=v"(r) : "v"(lo), "v"(hi)); return r; }
; __device__ __forceinline__ void norm_phase(const Params& P, unsigned char* ws, int layer, int which, int nrows, bool first, int lane, int wave, const float* pend_part, int pend_ns, const float* pend_gate) {
;     ...
; #pragma unroll
;         for (int r = 0; r < NR; ++r)
; #pragma unroll
;             for (int j = 0; j < 2; ++j)
; #pragma unroll
;                 for (int q = 0; q < 2; ++q) ss[r] += (v[r][j][q][0] * v[r][j][q][0] + v[r][j][q][1] * v[r][j][q][1]) + (v[r][j][q][2] * v[r][j][q][2] + v[r][j][q][3] * v[r][j][q][3]);
; #pragma unroll
;         for (int r = 0; r < NR; ++r) { const int row = row0 + r * NGW;
;             const float rstd = rsqrtf(wave_sum(ss[r], lane) * (1.0f / DM) + EPS);
;             const float* mod = (const float*)(ws + WS_MOD) + (size_t)(layer * 9 + (row >> 12)) * 6144 + which * 3 * DM;
; #pragma unroll
;             for (int j = 0; j < 2; ++j) { const int col = 8 * lane + 512 * j; u32x4 hw, xw;
; #pragma unroll
;                 for (int q = 0; q < 2; ++q) {
;                     const f32x4 g4 = *(const f32x4*)(g + col + 4 * q), sh = *(const f32x4*)(mod + col + 4 * q), sc = *(const f32x4*)(mod + DM + col + 4 * q);
;                     const f32x4 h = (v[r][j][q] * rstd) * g4 * (sc + 1.0f) + sh;
;                     if (q == 0) { hw.x = cvt_pk_bf16(h[0], h[1]); hw.y = cvt_pk_bf16(h[2], h[3]); xw.x = cvt_pk_bf16(v[r][j][q][0], v[r][j][q][1]); xw.y = cvt_pk_bf16(v[r][j][q][2], v[r][j][q][3]); }
;                     else { hw.z = cvt_pk_bf16(h[0], h[1]); hw.w = cvt_pk_bf16(h[2], h[3]); xw.z = cvt_pk_bf16(v[r][j][q][0], v[r][j][q][1]); xw.w = cvt_pk_bf16(v[r][j][q][2], v[r][j][q][3]); }
;                 }
;                 *(u32x4*)(H + (size_t)row * DM + col) = hw;
	ds_read_b128 v[32:35], v15 offset:0
	ds_read_b128 v[36:39], v15 offset:16
	ds_read_b128 v[40:43], v15 offset:2048
	ds_read_b128 v[44:47], v15 offset:2064
	ds_read_b128 v[48:51], v15 offset:32768
	ds_read_b128 v[52:55], v15 offset:32784
	ds_read_b128 v[56:59], v15 offset:34816
	ds_read_b128 v[60:63], v15 offset:34832
	v_lshlrev_b32_e32 v128, 16, v64
	v_and_b32_e32 v129, 0xffff0000, v64
	v_lshlrev_b32_e32 v130, 16, v65
	v_and_b32_e32 v131, 0xffff0000, v65
	v_lshlrev_b32_e32 v132, 16, v66
	v_and_b32_e32 v133, 0xffff0000, v66
	v_lshlrev_b32_e32 v134, 16, v67
	v_and_b32_e32 v135, 0xffff0000, v67
	v_lshlrev_b32_e32 v136, 16, v68
	v_and_b32_e32 v137, 0xffff0000, v68
	v_lshlrev_b32_e32 v138, 16, v69
	v_and_b32_e32 v139, 0xffff0000, v69
	v_lshlrev_b32_e32 v140, 16, v70
	v_and_b32_e32 v141, 0xffff0000, v70
	v_lshlrev_b32_e32 v142, 16, v71
	v_and_b32_e32 v143, 0xffff0000, v71
	v_lshlrev_b32_e32 v144, 16, v72
	v_and_b32_e32 v145, 0xffff0000, v72
	v_lshlrev_b32_e32 v146, 16, v73
	v_and_b32_e32 v147, 0xffff0000, v73
	v_lshlrev_b32_e32 v148, 16, v74
	v_and_b32_e32 v149, 0xffff0000, v74
	v_lshlrev_b32_e32 v150, 16, v75
	v_and_b32_e32 v151, 0xffff0000, v75
	v_lshlrev_b32_e32 v152, 16, v76
	v_and_b32_e32 v153, 0xffff0000, v76
	v_lshlrev_b32_e32 v154, 16, v77
	v_and_b32_e32 v155, 0xffff0000, v77
	v_lshlrev_b32_e32 v156, 16, v78
	v_and_b32_e32 v157, 0xffff0000, v78
	v_lshlrev_b32_e32 v158, 16, v79
	v_and_b32_e32 v159, 0xffff0000, v79
	v_pk_mul_f32 v[160:161], v[128:129], v[128:129]
	v_pk_mul_f32 v[162:163], v[144:145], v[144:145]
	v_pk_fma_f32 v[160:161], v[130:131], v[130:131], v[160:161]
	v_pk_fma_f32 v[162:163], v[146:147], v[146:147], v[162:163]
	v_pk_fma_f32 v[160:161], v[132:133], v[132:133], v[160:161]
	v_pk_fma_f32 v[162:163], v[148:149], v[148:149], v[162:163]
	v_pk_fma_f32 v[160:161], v[134:135], v[134:135], v[160:161]
	v_pk_fma_f32 v[162:163], v[150:151], v[150:151], v[162:163]
	v_pk_fma_f32 v[160:161], v[136:137], v[136:137], v[160:161]
	v_pk_fma_f32 v[162:163], v[152:153], v[152:153], v[162:163]
	v_pk_fma_f32 v[160:161], v[138:139], v[138:139], v[160:161]
	v_pk_fma_f32 v[162:163], v[154:155], v[154:155], v[162:163]
	v_pk_fma_f32 v[160:161], v[140:141], v[140:141], v[160:161]
	v_pk_fma_f32 v[162:163], v[156:157], v[156:157], v[162:163]
	v_pk_fma_f32 v[160:161], v[142:143], v[142:143], v[160:161]
	v_pk_fma_f32 v[162:163], v[158:159], v[158:159], v[162:163]
	v_add_f32_e32 v160, v160, v161
	v_add_f32_e32 v162, v162, v163
	ds_bpermute_b32 v164, v5, v160
	ds_bpermute_b32 v165, v5, v162
	s_waitcnt lgkmcnt(0)
	v_add_f32_e32 v160, v160, v164
	v_add_f32_e32 v162, v162, v165
	ds_bpermute_b32 v164, v6, v160
	ds_bpermute_b32 v165, v6, v162
	s_waitcnt lgkmcnt(0)
	v_add_f32_e32 v160, v160, v164
	v_add_f32_e32 v162, v162, v165
	ds_bpermute_b32 v164, v7, v160
	ds_bpermute_b32 v165, v7, v162
	s_waitcnt lgkmcnt(0)
	v_add_f32_e32 v160, v160, v164
	v_add_f32_e32 v162, v162, v165
	ds_bpermute_b32 v164, v9, v160
	ds_bpermute_b32 v165, v9, v162
	s_waitcnt lgkmcnt(0)
	v_add_f32_e32 v160, v160, v164
	v_add_f32_e32 v162, v162, v165
	ds_bpermute_b32 v164, v10, v160
	ds_bpermute_b32 v165, v10, v162
	s_waitcnt lgkmcnt(0)
	v_add_f32_e32 v160, v160, v164
	v_add_f32_e32 v162, v162, v165
	ds_bpermute_b32 v164, v11, v160
	ds_bpermute_b32 v165, v11, v162
	s_waitcnt lgkmcnt(0)
	v_add_f32_e32 v160, v160, v164
	v_add_f32_e32 v162, v162, v165
	v_fmamk_f32 v160, v160, 0x3a800000, v194
	v_fmamk_f32 v162, v162, 0x3a800000, v194
	v_rsq_f32_e32 v160, v160
	v_rsq_f32_e32 v162, v162
	v_pk_add_f32 v[48:49], v[48:49], 1.0 op_sel_hi:[1,0]
	v_pk_add_f32 v[50:51], v[50:51], 1.0 op_sel_hi:[1,0]
	v_pk_add_f32 v[52:53], v[52:53], 1.0 op_sel_hi:[1,0]
	v_pk_add_f32 v[54:55], v[54:55], 1.0 op_sel_hi:[1,0]
	v_pk_add_f32 v[56:57], v[56:57], 1.0 op_sel_hi:[1,0]
	v_pk_add_f32 v[58:59], v[58:59], 1.0 op_sel_hi:[1,0]
	v_pk_add_f32 v[60:61], v[60:61], 1.0 op_sel_hi:[1,0]
	v_pk_add_f32 v[62:63], v[62:63], 1.0 op_sel_hi:[1,0]
	v_pk_mul_f32 v[128:129], v[160:161], v[128:129] op_sel_hi:[0,1]
	v_pk_mul_f32 v[130:131], v[160:161], v[130:131] op_sel_hi:[0,1]
	v_pk_mul_f32 v[132:133], v[160:161], v[132:133] op_sel_hi:[0,1]
	v_pk_mul_f32 v[134:135], v[160:161], v[134:135] op_sel_hi:[0,1]
	v_pk_mul_f32 v[136:137], v[160:161], v[136:137] op_sel_hi:[0,1]
	v_pk_mul_f32 v[138:139], v[160:161], v[138:139] op_sel_hi:[0,1]
	v_pk_mul_f32 v[140:141], v[160:161], v[140:141] op_sel_hi:[0,1]
	v_pk_mul_f32 v[142:143], v[160:161], v[142:143] op_sel_hi:[0,1]
	v_pk_mul_f32 v[128:129], v[16:17], v[128:129]
	v_pk_mul_f32 v[130:131], v[18:19], v[130:131]
	v_pk_mul_f32 v[132:133], v[20:21], v[132:133]
	v_pk_mul_f32 v[134:135], v[22:23], v[134:135]
	v_pk_mul_f32 v[136:137], v[24:25], v[136:137]
	v_pk_mul_f32 v[138:139], v[26:27], v[138:139]
	v_pk_mul_f32 v[140:141], v[28:29], v[140:141]
	v_pk_mul_f32 v[142:143], v[30:31], v[142:143]
	v_pk_fma_f32 v[128:129], v[48:49], v[128:129], v[32:33]
	v_pk_fma_f32 v[130:131], v[50:51], v[130:131], v[34:35]
	v_pk_fma_f32 v[132:133], v[52:53], v[132:133], v[36:37]
	v_pk_fma_f32 v[134:135], v[54:55], v[134:135], v[38:39]
	v_pk_fma_f32 v[136:137], v[56:57], v[136:137], v[40:41]
	v_pk_fma_f32 v[138:139], v[58:59], v[138:139], v[42:43]
	v_pk_fma_f32 v[140:141], v[60:61], v[140:141], v[44:45]
	v_pk_fma_f32 v[142:143], v[62:63], v[142:143], v[46:47]
	v_cvt_pk_bf16_f32 v176, v128, v129
	v_cvt_pk_bf16_f32 v177, v130, v131
	v_cvt_pk_bf16_f32 v178, v132, v133
	v_cvt_pk_bf16_f32 v179, v134, v135
	v_cvt_pk_bf16_f32 v180, v136, v137
	v_cvt_pk_bf16_f32 v181, v138, v139
	v_cvt_pk_bf16_f32 v182, v140, v141
	v_cvt_pk_bf16_f32 v183, v142, v143
	s_add_i32 s10, s98, 0x8
	s_lshl_b32 s10, s10, 11
	s_add_u32 s28, s26, s10
; __device__ __forceinline__ void norm_phase(const Params& P, unsigned char* ws, int layer, int which, int nrows, bool first, int lane, int wave, const float* pend_part, int pend_ns, const float* pend_gate) {
;     ...
;         for (int r = 0; r < NR; ++r) { const int row = row0 + r * NGW; ss[r] = 0.f;
; #pragma unroll
;             for (int j = 0; j < 2; ++j) { const int col = 8 * lane + 512 * j;
;                 if (first) { v[r][j][0] = *(const f32x4*)(P.in[I_X] + (size_t)row * DM + col); v[r][j][1] = *(const f32x4*)(P.in[I_X] + (size_t)row * DM + col + 4); }
;                 else { const u32x4 w = *(const u32x4*)(XB + (size_t)row * DM + col); v[r][j][0] = bf4_to_f32((u32x2){w.x, w.y}); v[r][j][1] = bf4_to_f32((u32x2){w.z, w.w}); } } }
; #pragma unroll
;         for (int r = 0; r < NR; ++r)
; #pragma unroll
;             for (int j = 0; j < 2; ++j)
; #pragma unroll
;                 for (int q = 0; q < 2; ++q) ss[r] += (v[r][j][q][0] * v[r][j][q][0] + v[r][j][q][1] * v[r][j][q][1]) + (v[r][j][q][2] * v[r][j][q][2] + v[r][j][q][3] * v[r][j][q][3]);
; #pragma unroll
;         for (int r = 0; r < NR; ++r) { const int row = row0 + r * NGW;
;             const float rstd = rsqrtf(wave_sum(ss[r], lane) * (1.0f / DM) + EPS);
;             const float* mod = (const float*)(ws + WS_MOD) + (size_t)(layer * 9 + (row >> 12)) * 6144 + which * 3 * DM;
; #pragma unroll
;             for (int j = 0; j < 2; ++j) { const int col = 8 * lane + 512 * j; u32x4 hw, xw;
; #pragma unroll
;                 for (int q = 0; q < 2; ++q) {
;                     const f32x4 g4 = *(const f32x4*)(g + col + 4 * q), sh = *(const f32x4*)(mod + col + 4 * q), sc = *(const f32x4*)(mod + DM + col + 4 * q);
;                     const f32x4 h = (v[r][j][q] * rstd) * g4 * (sc + 1.0f) + sh;
;                     if (q == 0) { hw.x = cvt_pk_bf16(h[0], h[1]); hw.y = cvt_pk_bf16(h[2], h[3]); xw.x = cvt_pk_bf16(v[r][j][q][0], v[r][j][q][1]); xw.y = cvt_pk_bf16(v[r][j][q][2], v[r][j][q][3]); }
;                     else { hw.z = cvt_pk_bf16(h[0], h[1]); hw.w = cvt_pk_bf16(h[2], h[3]); xw.z = cvt_pk_bf16(v[r][j][q][0], v[r][j][q][1]); xw.w = cvt_pk_bf16(v[r][j][q][2], v[r][j][q][3]); }
;                 }
;                 *(u32x4*)(H + (size_t)row * DM + col) = hw;
	s_addc_u32 s29, s27, 0
	global_store_dwordx4 v2, v[176:179], s[28:29] sc1
	global_store_dwordx4 v2, v[180:183], s[28:29] offset:1024 sc1
	v_pk_mul_f32 v[144:145], v[162:163], v[144:145] op_sel_hi:[0,1]
	v_pk_mul_f32 v[146:147], v[162:163], v[146:147] op_sel_hi:[0,1]
	v_pk_mul_f32 v[148:149], v[162:163], v[148:149] op_sel_hi:[0,1]
	v_pk_mul_f32 v[150:151], v[162:163], v[150:151] op_sel_hi:[0,1]
	v_pk_mul_f32 v[152:153], v[162:163], v[152:153] op_sel_hi:[0,1]
	v_pk_mul_f32 v[154:155], v[162:163], v[154:155] op_sel_hi:[0,1]
	v_pk_mul_f32 v[156:157], v[162:163], v[156:157] op_sel_hi:[0,1]
	v_pk_mul_f32 v[158:159], v[162:163], v[158:159] op_sel_hi:[0,1]
	v_pk_mul_f32 v[144:145], v[16:17], v[144:145]
	v_pk_mul_f32 v[146:147], v[18:19], v[146:147]
	v_pk_mul_f32 v[148:149], v[20:21], v[148:149]
	v_pk_mul_f32 v[150:151], v[22:23], v[150:151]
	v_pk_mul_f32 v[152:153], v[24:25], v[152:153]
	v_pk_mul_f32 v[154:155], v[26:27], v[154:155]
	v_pk_mul_f32 v[156:157], v[28:29], v[156:157]
	v_pk_mul_f32 v[158:159], v[30:31], v[158:159]
	v_pk_fma_f32 v[144:145], v[48:49], v[144:145], v[32:33]
	v_pk_fma_f32 v[146:147], v[50:51], v[146:147], v[34:35]
	v_pk_fma_f32 v[148:149], v[52:53], v[148:149], v[36:37]
	v_pk_fma_f32 v[150:151], v[54:55], v[150:151], v[38:39]
	v_pk_fma_f32 v[152:153], v[56:57], v[152:153], v[40:41]
	v_pk_fma_f32 v[154:155], v[58:59], v[154:155], v[42:43]
	v_pk_fma_f32 v[156:157], v[60:61], v[156:157], v[44:45]
	v_pk_fma_f32 v[158:159], v[62:63], v[158:159], v[46:47]
	v_cvt_pk_bf16_f32 v184, v144, v145
	v_cvt_pk_bf16_f32 v185, v146, v147
	v_cvt_pk_bf16_f32 v186, v148, v149
	v_cvt_pk_bf16_f32 v187, v150, v151
	v_cvt_pk_bf16_f32 v188, v152, v153
	v_cvt_pk_bf16_f32 v189, v154, v155
	v_cvt_pk_bf16_f32 v190, v156, v157
	v_cvt_pk_bf16_f32 v191, v158, v159
	s_add_i32 s10, s98, 0x9
	s_lshl_b32 s10, s10, 11
	s_add_u32 s28, s26, s10
	s_addc_u32 s29, s27, 0
	global_store_dwordx4 v2, v[184:187], s[28:29] sc1
	global_store_dwordx4 v2, v[188:191], s[28:29] offset:1024 sc1
	s_waitcnt vmcnt(20)
	ds_read_b128 v[32:35], v15 offset:0
	ds_read_b128 v[36:39], v15 offset:16
	ds_read_b128 v[40:43], v15 offset:2048
	ds_read_b128 v[44:47], v15 offset:2064
	ds_read_b128 v[48:51], v15 offset:32768
	ds_read_b128 v[52:55], v15 offset:32784
	ds_read_b128 v[56:59], v15 offset:34816
	ds_read_b128 v[60:63], v15 offset:34832
	v_lshlrev_b32_e32 v128, 16, v80
	v_and_b32_e32 v129, 0xffff0000, v80
	v_lshlrev_b32_e32 v130, 16, v81
	v_and_b32_e32 v131, 0xffff0000, v81
	v_lshlrev_b32_e32 v132, 16, v82
	v_and_b32_e32 v133, 0xffff0000, v82
	v_lshlrev_b32_e32 v134, 16, v83
	v_and_b32_e32 v135, 0xffff0000, v83
	v_lshlrev_b32_e32 v136, 16, v84
	v_and_b32_e32 v137, 0xffff0000, v84
	v_lshlrev_b32_e32 v138, 16, v85
	v_and_b32_e32 v139, 0xffff0000, v85
	v_lshlrev_b32_e32 v140, 16, v86
	v_and_b32_e32 v141, 0xffff0000, v86
	v_lshlrev_b32_e32 v142, 16, v87
	v_and_b32_e32 v143, 0xffff0000, v87
	v_lshlrev_b32_e32 v144, 16, v88
	v_and_b32_e32 v145, 0xffff0000, v88
	v_lshlrev_b32_e32 v146, 16, v89
	v_and_b32_e32 v147, 0xffff0000, v89
	v_lshlrev_b32_e32 v148, 16, v90
	v_and_b32_e32 v149, 0xffff0000, v90
	v_lshlrev_b32_e32 v150, 16, v91
	v_and_b32_e32 v151, 0xffff0000, v91
	v_lshlrev_b32_e32 v152, 16, v92
	v_and_b32_e32 v153, 0xffff0000, v92
	v_lshlrev_b32_e32 v154, 16, v93
	v_and_b32_e32 v155, 0xffff0000, v93
	v_lshlrev_b32_e32 v156, 16, v94
	v_and_b32_e32 v157, 0xffff0000, v94
	v_lshlrev_b32_e32 v158, 16, v95
	v_and_b32_e32 v159, 0xffff0000, v95
	v_pk_mul_f32 v[160:161], v[128:129], v[128:129]
	v_pk_mul_f32 v[162:163], v[144:145], v[144:145]
	v_pk_fma_f32 v[160:161], v[130:131], v[130:131], v[160:161]
	v_pk_fma_f32 v[162:163], v[146:147], v[146:147], v[162:163]
	v_pk_fma_f32 v[160:161], v[132:133], v[132:133], v[160:161]
	v_pk_fma_f32 v[162:163], v[148:149], v[148:149], v[162:163]
	v_pk_fma_f32 v[160:161], v[134:135], v[134:135], v[160:161]
	v_pk_fma_f32 v[162:163], v[150:151], v[150:151], v[162:163]
	v_pk_fma_f32 v[160:161], v[136:137], v[136:137], v[160:161]
	v_pk_fma_f32 v[162:163], v[152:153], v[152:153], v[162:163]
	v_pk_fma_f32 v[160:161], v[138:139], v[138:139], v[160:161]
	v_pk_fma_f32 v[162:163], v[154:155], v[154:155], v[162:163]
	v_pk_fma_f32 v[160:161], v[140:141], v[140:141], v[160:161]
	v_pk_fma_f32 v[162:163], v[156:157], v[156:157], v[162:163]
	v_pk_fma_f32 v[160:161], v[142:143], v[142:143], v[160:161]
	v_pk_fma_f32 v[162:163], v[158:159], v[158:159], v[162:163]
	v_add_f32_e32 v160, v160, v161
	v_add_f32_e32 v162, v162, v163
	ds_bpermute_b32 v164, v5, v160
	ds_bpermute_b32 v165, v5, v162
	s_waitcnt lgkmcnt(0)
	v_add_f32_e32 v160, v160, v164
	v_add_f32_e32 v162, v162, v165
	ds_bpermute_b32 v164, v6, v160
	ds_bpermute_b32 v165, v6, v162
	s_waitcnt lgkmcnt(0)
	v_add_f32_e32 v160, v160, v164
	v_add_f32_e32 v162, v162, v165
	ds_bpermute_b32 v164, v7, v160
	ds_bpermute_b32 v165, v7, v162
	s_waitcnt lgkmcnt(0)
	v_add_f32_e32 v160, v160, v164
	v_add_f32_e32 v162, v162, v165
	ds_bpermute_b32 v164, v9, v160
	ds_bpermute_b32 v165, v9, v162
	s_waitcnt lgkmcnt(0)
	v_add_f32_e32 v160, v160, v164
	v_add_f32_e32 v162, v162, v165
	ds_bpermute_b32 v164, v10, v160
	ds_bpermute_b32 v165, v10, v162
	s_waitcnt lgkmcnt(0)
	v_add_f32_e32 v160, v160, v164
	v_add_f32_e32 v162, v162, v165
	ds_bpermute_b32 v164, v11, v160
	ds_bpermute_b32 v165, v11, v162
	s_waitcnt lgkmcnt(0)
; __device__ __forceinline__ unsigned cvt_pk_bf16(float lo, float hi) { unsigned r; asm volatile("v_cvt_pk_bf16_f32 %0, %1, %2" : "=v"(r) : "v"(lo), "v"(hi)); return r; }
; __device__ __forceinline__ void norm_phase(const Params& P, unsigned char* ws, int layer, int which, int nrows, bool first, int lane, int wave, const float* pend_part, int pend_ns, const float* pend_gate) {
;     ...
; #pragma unroll
;         for (int r = 0; r < NR; ++r)
; #pragma unroll
;             for (int j = 0; j < 2; ++j)
; #pragma unroll
;                 for (int q = 0; q < 2; ++q) ss[r] += (v[r][j][q][0] * v[r][j][q][0] + v[r][j][q][1] * v[r][j][q][1]) + (v[r][j][q][2] * v[r][j][q][2] + v[r][j][q][3] * v[r][j][q][3]);
; #pragma unroll
;         for (int r = 0; r < NR; ++r) { const int row = row0 + r * NGW;
;             const float rstd = rsqrtf(wave_sum(ss[r], lane) * (1.0f / DM) + EPS);
;             const float* mod = (const float*)(ws + WS_MOD) + (size_t)(layer * 9 + (row >> 12)) * 6144 + which * 3 * DM;
; #pragma unroll
;             for (int j = 0; j < 2; ++j) { const int col = 8 * lane + 512 * j; u32x4 hw, xw;
; #pragma unroll
;                 for (int q = 0; q < 2; ++q) {
;                     const f32x4 g4 = *(const f32x4*)(g + col + 4 * q), sh = *(const f32x4*)(mod + col + 4 * q), sc = *(const f32x4*)(mod + DM + col + 4 * q);
;                     const f32x4 h = (v[r][j][q] * rstd) * g4 * (sc + 1.0f) + sh;
;                     if (q == 0) { hw.x = cvt_pk_bf16(h[0], h[1]); hw.y = cvt_pk_bf16(h[2], h[3]); xw.x = cvt_pk_bf16(v[r][j][q][0], v[r][j][q][1]); xw.y = cvt_pk_bf16(v[r][j][q][2], v[r][j][q][3]); }
;                     else { hw.z = cvt_pk_bf16(h[0], h[1]); hw.w = cvt_pk_bf16(h[2], h[3]); xw.z = cvt_pk_bf16(v[r][j][q][0], v[r][j][q][1]); xw.w = cvt_pk_bf16(v[r][j][q][2], v[r][j][q][3]); }
;                 }
;                 *(u32x4*)(H + (size_t)row * DM + col) = hw;
	v_add_f32_e32 v160, v160, v164
	v_add_f32_e32 v162, v162, v165
	v_fmamk_f32 v160, v160, 0x3a800000, v194
	v_fmamk_f32 v162, v162, 0x3a800000, v194
	v_rsq_f32_e32 v160, v160
	v_rsq_f32_e32 v162, v162
	v_pk_add_f32 v[48:49], v[48:49], 1.0 op_sel_hi:[1,0]
	v_pk_add_f32 v[50:51], v[50:51], 1.0 op_sel_hi:[1,0]
	v_pk_add_f32 v[52:53], v[52:53], 1.0 op_sel_hi:[1,0]
	v_pk_add_f32 v[54:55], v[54:55], 1.0 op_sel_hi:[1,0]
	v_pk_add_f32 v[56:57], v[56:57], 1.0 op_sel_hi:[1,0]
	v_pk_add_f32 v[58:59], v[58:59], 1.0 op_sel_hi:[1,0]
	v_pk_add_f32 v[60:61], v[60:61], 1.0 op_sel_hi:[1,0]
	v_pk_add_f32 v[62:63], v[62:63], 1.0 op_sel_hi:[1,0]
	v_pk_mul_f32 v[128:129], v[160:161], v[128:129] op_sel_hi:[0,1]
	v_pk_mul_f32 v[130:131], v[160:161], v[130:131] op_sel_hi:[0,1]
	v_pk_mul_f32 v[132:133], v[160:161], v[132:133] op_sel_hi:[0,1]
	v_pk_mul_f32 v[134:135], v[160:161], v[134:135] op_sel_hi:[0,1]
	v_pk_mul_f32 v[136:137], v[160:161], v[136:137] op_sel_hi:[0,1]
	v_pk_mul_f32 v[138:139], v[160:161], v[138:139] op_sel_hi:[0,1]
	v_pk_mul_f32 v[140:141], v[160:161], v[140:141] op_sel_hi:[0,1]
	v_pk_mul_f32 v[142:143], v[160:161], v[142:143] op_sel_hi:[0,1]
	v_pk_mul_f32 v[128:129], v[16:17], v[128:129]
	v_pk_mul_f32 v[130:131], v[18:19], v[130:131]
	v_pk_mul_f32 v[132:133], v[20:21], v[132:133]
	v_pk_mul_f32 v[134:135], v[22:23], v[134:135]
	v_pk_mul_f32 v[136:137], v[24:25], v[136:137]
	v_pk_mul_f32 v[138:139], v[26:27], v[138:139]
	v_pk_mul_f32 v[140:141], v[28:29], v[140:141]
	v_pk_mul_f32 v[142:143], v[30:31], v[142:143]
	v_pk_fma_f32 v[128:129], v[48:49], v[128:129], v[32:33]
	v_pk_fma_f32 v[130:131], v[50:51], v[130:131], v[34:35]
	v_pk_fma_f32 v[132:133], v[52:53], v[132:133], v[36:37]
	v_pk_fma_f32 v[134:135], v[54:55], v[134:135], v[38:39]
	v_pk_fma_f32 v[136:137], v[56:57], v[136:137], v[40:41]
	v_pk_fma_f32 v[138:139], v[58:59], v[138:139], v[42:43]
	v_pk_fma_f32 v[140:141], v[60:61], v[140:141], v[44:45]
	v_pk_fma_f32 v[142:143], v[62:63], v[142:143], v[46:47]
	v_cvt_pk_bf16_f32 v176, v128, v129
	v_cvt_pk_bf16_f32 v177, v130, v131
	v_cvt_pk_bf16_f32 v178, v132, v133
	v_cvt_pk_bf16_f32 v179, v134, v135
	v_cvt_pk_bf16_f32 v180, v136, v137
	v_cvt_pk_bf16_f32 v181, v138, v139
	v_cvt_pk_bf16_f32 v182, v140, v141
	v_cvt_pk_bf16_f32 v183, v142, v143
	s_add_i32 s10, s98, 0xa
	s_lshl_b32 s10, s10, 11
	s_add_u32 s28, s26, s10
	s_addc_u32 s29, s27, 0
	global_store_dwordx4 v2, v[176:179], s[28:29] sc1
	global_store_dwordx4 v2, v[180:183], s[28:29] offset:1024 sc1
	v_pk_mul_f32 v[144:145], v[162:163], v[144:145] op_sel_hi:[0,1]
	v_pk_mul_f32 v[146:147], v[162:163], v[146:147] op_sel_hi:[0,1]
	v_pk_mul_f32 v[148:149], v[162:163], v[148:149] op_sel_hi:[0,1]
	v_pk_mul_f32 v[150:151], v[162:163], v[150:151] op_sel_hi:[0,1]
	v_pk_mul_f32 v[152:153], v[162:163], v[152:153] op_sel_hi:[0,1]
	v_pk_mul_f32 v[154:155], v[162:163], v[154:155] op_sel_hi:[0,1]
	v_pk_mul_f32 v[156:157], v[162:163], v[156:157] op_sel_hi:[0,1]
	v_pk_mul_f32 v[158:159], v[162:163], v[158:159] op_sel_hi:[0,1]
	v_pk_mul_f32 v[144:145], v[16:17], v[144:145]
	v_pk_mul_f32 v[146:147], v[18:19], v[146:147]
	v_pk_mul_f32 v[148:149], v[20:21], v[148:149]
	v_pk_mul_f32 v[150:151], v[22:23], v[150:151]
	v_pk_mul_f32 v[152:153], v[24:25], v[152:153]
	v_pk_mul_f32 v[154:155], v[26:27], v[154:155]
	v_pk_mul_f32 v[156:157], v[28:29], v[156:157]
	v_pk_mul_f32 v[158:159], v[30:31], v[158:159]
	v_pk_fma_f32 v[144:145], v[48:49], v[144:145], v[32:33]
	v_pk_fma_f32 v[146:147], v[50:51], v[146:147], v[34:35]
	v_pk_fma_f32 v[148:149], v[52:53], v[148:149], v[36:37]
	v_pk_fma_f32 v[150:151], v[54:55], v[150:151], v[38:39]
	v_pk_fma_f32 v[152:153], v[56:57], v[152:153], v[40:41]
	v_pk_fma_f32 v[154:155], v[58:59], v[154:155], v[42:43]
	v_pk_fma_f32 v[156:157], v[60:61], v[156:157], v[44:45]
	v_pk_fma_f32 v[158:159], v[62:63], v[158:159], v[46:47]
	v_cvt_pk_bf16_f32 v184, v144, v145
	v_cvt_pk_bf16_f32 v185, v146, v147
	v_cvt_pk_bf16_f32 v186, v148, v149
	v_cvt_pk_bf16_f32 v187, v150, v151
	v_cvt_pk_bf16_f32 v188, v152, v153
	v_cvt_pk_bf16_f32 v189, v154, v155
	v_cvt_pk_bf16_f32 v190, v156, v157
	v_cvt_pk_bf16_f32 v191, v158, v159
	s_add_i32 s10, s98, 0xb
	s_lshl_b32 s10, s10, 11
	s_add_u32 s28, s26, s10
	s_addc_u32 s29, s27, 0
	global_store_dwordx4 v2, v[184:187], s[28:29] sc1
	global_store_dwordx4 v2, v[188:191], s[28:29] offset:1024 sc1
	s_waitcnt vmcnt(16)
; __device__ __forceinline__ unsigned cvt_pk_bf16(float lo, float hi) { unsigned r; asm volatile("v_cvt_pk_bf16_f32 %0, %1, %2" : "=v"(r) : "v"(lo), "v"(hi)); return r; }
; __device__ __forceinline__ void norm_phase(const Params& P, unsigned char* ws, int layer, int which, int nrows, bool first, int lane, int wave, const float* pend_part, int pend_ns, const float* pend_gate) {
;     ...
; #pragma unroll
;         for (int r = 0; r < NR; ++r)
; #pragma unroll
;             for (int j = 0; j < 2; ++j)
; #pragma unroll
;                 for (int q = 0; q < 2; ++q) ss[r] += (v[r][j][q][0] * v[r][j][q][0] + v[r][j][q][1] * v[r][j][q][1]) + (v[r][j][q][2] * v[r][j][q][2] + v[r][j][q][3] * v[r][j][q][3]);
; #pragma unroll
;         for (int r = 0; r < NR; ++r) { const int row = row0 + r * NGW;
;             const float rstd = rsqrtf(wave_sum(ss[r], lane) * (1.0f / DM) + EPS);
;             const float* mod = (const float*)(ws + WS_MOD) + (size_t)(layer * 9 + (row >> 12)) * 6144 + which * 3 * DM;
; #pragma unroll
;             for (int j = 0; j < 2; ++j) { const int col = 8 * lane + 512 * j; u32x4 hw, xw;
; #pragma unroll
;                 for (int q = 0; q < 2; ++q) {
;                     const f32x4 g4 = *(const f32x4*)(g + col + 4 * q), sh = *(const f32x4*)(mod + col + 4 * q), sc = *(const f32x4*)(mod + DM + col + 4 * q);
;                     const f32x4 h = (v[r][j][q] * rstd) * g4 * (sc + 1.0f) + sh;
;                     if (q == 0) { hw.x = cvt_pk_bf16(h[0], h[1]); hw.y = cvt_pk_bf16(h[2], h[3]); xw.x = cvt_pk_bf16(v[r][j][q][0], v[r][j][q][1]); xw.y = cvt_pk_bf16(v[r][j][q][2], v[r][j][q][3]); }
;                     else { hw.z = cvt_pk_bf16(h[0], h[1]); hw.w = cvt_pk_bf16(h[2], h[3]); xw.z = cvt_pk_bf16(v[r][j][q][0], v[r][j][q][1]); xw.w = cvt_pk_bf16(v[r][j][q][2], v[r][j][q][3]); }
;                 }
;                 *(u32x4*)(H + (size_t)row * DM + col) = hw;
	ds_read_b128 v[32:35], v15 offset:0
	ds_read_b128 v[36:39], v15 offset:16
	ds_read_b128 v[40:43], v15 offset:2048
	ds_read_b128 v[44:47], v15 offset:2064
	ds_read_b128 v[48:51], v15 offset:32768
	ds_read_b128 v[52:55], v15 offset:32784
	ds_read_b128 v[56:59], v15 offset:34816
	ds_read_b128 v[60:63], v15 offset:34832
	v_lshlrev_b32_e32 v128, 16, v96
	v_and_b32_e32 v129, 0xffff0000, v96
	v_lshlrev_b32_e32 v130, 16, v97
	v_and_b32_e32 v131, 0xffff0000, v97
	v_lshlrev_b32_e32 v132, 16, v98
	v_and_b32_e32 v133, 0xffff0000, v98
	v_lshlrev_b32_e32 v134, 16, v99
	v_and_b32_e32 v135, 0xffff0000, v99
	v_lshlrev_b32_e32 v136, 16, v100
	v_and_b32_e32 v137, 0xffff0000, v100
	v_lshlrev_b32_e32 v138, 16, v101
	v_and_b32_e32 v139, 0xffff0000, v101
	v_lshlrev_b32_e32 v140, 16, v102
	v_and_b32_e32 v141, 0xffff0000, v102
	v_lshlrev_b32_e32 v142, 16, v103
	v_and_b32_e32 v143, 0xffff0000, v103
	v_lshlrev_b32_e32 v144, 16, v104
	v_and_b32_e32 v145, 0xffff0000, v104
	v_lshlrev_b32_e32 v146, 16, v105
	v_and_b32_e32 v147, 0xffff0000, v105
	v_lshlrev_b32_e32 v148, 16, v106
	v_and_b32_e32 v149, 0xffff0000, v106
	v_lshlrev_b32_e32 v150, 16, v107
	v_and_b32_e32 v151, 0xffff0000, v107
	v_lshlrev_b32_e32 v152, 16, v108
	v_and_b32_e32 v153, 0xffff0000, v108
	v_lshlrev_b32_e32 v154, 16, v109
	v_and_b32_e32 v155, 0xffff0000, v109
	v_lshlrev_b32_e32 v156, 16, v110
	v_and_b32_e32 v157, 0xffff0000, v110
	v_lshlrev_b32_e32 v158, 16, v111
	v_and_b32_e32 v159, 0xffff0000, v111
	v_pk_mul_f32 v[160:161], v[128:129], v[128:129]
	v_pk_mul_f32 v[162:163], v[144:145], v[144:145]
	v_pk_fma_f32 v[160:161], v[130:131], v[130:131], v[160:161]
	v_pk_fma_f32 v[162:163], v[146:147], v[146:147], v[162:163]
	v_pk_fma_f32 v[160:161], v[132:133], v[132:133], v[160:161]
	v_pk_fma_f32 v[162:163], v[148:149], v[148:149], v[162:163]
	v_pk_fma_f32 v[160:161], v[134:135], v[134:135], v[160:161]
	v_pk_fma_f32 v[162:163], v[150:151], v[150:151], v[162:163]
	v_pk_fma_f32 v[160:161], v[136:137], v[136:137], v[160:161]
	v_pk_fma_f32 v[162:163], v[152:153], v[152:153], v[162:163]
	v_pk_fma_f32 v[160:161], v[138:139], v[138:139], v[160:161]
	v_pk_fma_f32 v[162:163], v[154:155], v[154:155], v[162:163]
	v_pk_fma_f32 v[160:161], v[140:141], v[140:141], v[160:161]
	v_pk_fma_f32 v[162:163], v[156:157], v[156:157], v[162:163]
	v_pk_fma_f32 v[160:161], v[142:143], v[142:143], v[160:161]
	v_pk_fma_f32 v[162:163], v[158:159], v[158:159], v[162:163]
	v_add_f32_e32 v160, v160, v161
	v_add_f32_e32 v162, v162, v163
	ds_bpermute_b32 v164, v5, v160
	ds_bpermute_b32 v165, v5, v162
	s_waitcnt lgkmcnt(0)
	v_add_f32_e32 v160, v160, v164
	v_add_f32_e32 v162, v162, v165
	ds_bpermute_b32 v164, v6, v160
	ds_bpermute_b32 v165, v6, v162
	s_waitcnt lgkmcnt(0)
	v_add_f32_e32 v160, v160, v164
	v_add_f32_e32 v162, v162, v165
	ds_bpermute_b32 v164, v7, v160
	ds_bpermute_b32 v165, v7, v162
	s_waitcnt lgkmcnt(0)
	v_add_f32_e32 v160, v160, v164
	v_add_f32_e32 v162, v162, v165
	ds_bpermute_b32 v164, v9, v160
	ds_bpermute_b32 v165, v9, v162
	s_waitcnt lgkmcnt(0)
	v_add_f32_e32 v160, v160, v164
	v_add_f32_e32 v162, v162, v165
	ds_bpermute_b32 v164, v10, v160
	ds_bpermute_b32 v165, v10, v162
	s_waitcnt lgkmcnt(0)
	v_add_f32_e32 v160, v160, v164
	v_add_f32_e32 v162, v162, v165
	ds_bpermute_b32 v164, v11, v160
	ds_bpermute_b32 v165, v11, v162
	s_waitcnt lgkmcnt(0)
	v_add_f32_e32 v160, v160, v164
	v_add_f32_e32 v162, v162, v165
	v_fmamk_f32 v160, v160, 0x3a800000, v194
	v_fmamk_f32 v162, v162, 0x3a800000, v194
	v_rsq_f32_e32 v160, v160
	v_rsq_f32_e32 v162, v162
	v_pk_add_f32 v[48:49], v[48:49], 1.0 op_sel_hi:[1,0]
	v_pk_add_f32 v[50:51], v[50:51], 1.0 op_sel_hi:[1,0]
	v_pk_add_f32 v[52:53], v[52:53], 1.0 op_sel_hi:[1,0]
	v_pk_add_f32 v[54:55], v[54:55], 1.0 op_sel_hi:[1,0]
	v_pk_add_f32 v[56:57], v[56:57], 1.0 op_sel_hi:[1,0]
	v_pk_add_f32 v[58:59], v[58:59], 1.0 op_sel_hi:[1,0]
	v_pk_add_f32 v[60:61], v[60:61], 1.0 op_sel_hi:[1,0]
	v_pk_add_f32 v[62:63], v[62:63], 1.0 op_sel_hi:[1,0]
	v_pk_mul_f32 v[128:129], v[160:161], v[128:129] op_sel_hi:[0,1]
	v_pk_mul_f32 v[130:131], v[160:161], v[130:131] op_sel_hi:[0,1]
	v_pk_mul_f32 v[132:133], v[160:161], v[132:133] op_sel_hi:[0,1]
	v_pk_mul_f32 v[134:135], v[160:161], v[134:135] op_sel_hi:[0,1]
	v_pk_mul_f32 v[136:137], v[160:161], v[136:137] op_sel_hi:[0,1]
	v_pk_mul_f32 v[138:139], v[160:161], v[138:139] op_sel_hi:[0,1]
	v_pk_mul_f32 v[140:141], v[160:161], v[140:141] op_sel_hi:[0,1]
	v_pk_mul_f32 v[142:143], v[160:161], v[142:143] op_sel_hi:[0,1]
	v_pk_mul_f32 v[128:129], v[16:17], v[128:129]
	v_pk_mul_f32 v[130:131], v[18:19], v[130:131]
	v_pk_mul_f32 v[132:133], v[20:21], v[132:133]
	v_pk_mul_f32 v[134:135], v[22:23], v[134:135]
	v_pk_mul_f32 v[136:137], v[24:25], v[136:137]
	v_pk_mul_f32 v[138:139], v[26:27], v[138:139]
	v_pk_mul_f32 v[140:141], v[28:29], v[140:141]
	v_pk_mul_f32 v[142:143], v[30:31], v[142:143]
	v_pk_fma_f32 v[128:129], v[48:49], v[128:129], v[32:33]
	v_pk_fma_f32 v[130:131], v[50:51], v[130:131], v[34:35]
	v_pk_fma_f32 v[132:133], v[52:53], v[132:133], v[36:37]
	v_pk_fma_f32 v[134:135], v[54:55], v[134:135], v[38:39]
	v_pk_fma_f32 v[136:137], v[56:57], v[136:137], v[40:41]
	v_pk_fma_f32 v[138:139], v[58:59], v[138:139], v[42:43]
	v_pk_fma_f32 v[140:141], v[60:61], v[140:141], v[44:45]
	v_pk_fma_f32 v[142:143], v[62:63], v[142:143], v[46:47]
	v_cvt_pk_bf16_f32 v176, v128, v129
	v_cvt_pk_bf16_f32 v177, v130, v131
	v_cvt_pk_bf16_f32 v178, v132, v133
	v_cvt_pk_bf16_f32 v179, v134, v135
	v_cvt_pk_bf16_f32 v180, v136, v137
	v_cvt_pk_bf16_f32 v181, v138, v139
	v_cvt_pk_bf16_f32 v182, v140, v141
	v_cvt_pk_bf16_f32 v183, v142, v143
	s_add_i32 s10, s98, 0xc
	s_lshl_b32 s10, s10, 11
; __device__ __forceinline__ void norm_phase(const Params& P, unsigned char* ws, int layer, int which, int nrows, bool first, int lane, int wave, const float* pend_part, int pend_ns, const float* pend_gate) {
;     ...
;         for (int r = 0; r < NR; ++r) { const int row = row0 + r * NGW; ss[r] = 0.f;
; #pragma unroll
;             for (int j = 0; j < 2; ++j) { const int col = 8 * lane + 512 * j;
;                 if (first) { v[r][j][0] = *(const f32x4*)(P.in[I_X] + (size_t)row * DM + col); v[r][j][1] = *(const f32x4*)(P.in[I_X] + (size_t)row * DM + col + 4); }
;                 else { const u32x4 w = *(const u32x4*)(XB + (size_t)row * DM + col); v[r][j][0] = bf4_to_f32((u32x2){w.x, w.y}); v[r][j][1] = bf4_to_f32((u32x2){w.z, w.w}); } } }
; #pragma unroll
;         for (int r = 0; r < NR; ++r)
; #pragma unroll
;             for (int j = 0; j < 2; ++j)
; #pragma unroll
;                 for (int q = 0; q < 2; ++q) ss[r] += (v[r][j][q][0] * v[r][j][q][0] + v[r][j][q][1] * v[r][j][q][1]) + (v[r][j][q][2] * v[r][j][q][2] + v[r][j][q][3] * v[r][j][q][3]);
; #pragma unroll
;         for (int r = 0; r < NR; ++r) { const int row = row0 + r * NGW;
;             const float rstd = rsqrtf(wave_sum(ss[r], lane) * (1.0f / DM) + EPS);
;             const float* mod = (const float*)(ws + WS_MOD) + (size_t)(layer * 9 + (row >> 12)) * 6144 + which * 3 * DM;
; #pragma unroll
;             for (int j = 0; j < 2; ++j) { const int col = 8 * lane + 512 * j; u32x4 hw, xw;
; #pragma unroll
;                 for (int q = 0; q < 2; ++q) {
;                     const f32x4 g4 = *(const f32x4*)(g + col + 4 * q), sh = *(const f32x4*)(mod + col + 4 * q), sc = *(const f32x4*)(mod + DM + col + 4 * q);
;                     const f32x4 h = (v[r][j][q] * rstd) * g4 * (sc + 1.0f) + sh;
;                     if (q == 0) { hw.x = cvt_pk_bf16(h[0], h[1]); hw.y = cvt_pk_bf16(h[2], h[3]); xw.x = cvt_pk_bf16(v[r][j][q][0], v[r][j][q][1]); xw.y = cvt_pk_bf16(v[r][j][q][2], v[r][j][q][3]); }
;                     else { hw.z = cvt_pk_bf16(h[0], h[1]); hw.w = cvt_pk_bf16(h[2], h[3]); xw.z = cvt_pk_bf16(v[r][j][q][0], v[r][j][q][1]); xw.w = cvt_pk_bf16(v[r][j][q][2], v[r][j][q][3]); }
;                 }
;                 *(u32x4*)(H + (size_t)row * DM + col) = hw;
	s_add_u32 s28, s26, s10
	s_addc_u32 s29, s27, 0
	global_store_dwordx4 v2, v[176:179], s[28:29] sc1
	global_store_dwordx4 v2, v[180:183], s[28:29] offset:1024 sc1
	v_pk_mul_f32 v[144:145], v[162:163], v[144:145] op_sel_hi:[0,1]
	v_pk_mul_f32 v[146:147], v[162:163], v[146:147] op_sel_hi:[0,1]
	v_pk_mul_f32 v[148:149], v[162:163], v[148:149] op_sel_hi:[0,1]
	v_pk_mul_f32 v[150:151], v[162:163], v[150:151] op_sel_hi:[0,1]
	v_pk_mul_f32 v[152:153], v[162:163], v[152:153] op_sel_hi:[0,1]
	v_pk_mul_f32 v[154:155], v[162:163], v[154:155] op_sel_hi:[0,1]
	v_pk_mul_f32 v[156:157], v[162:163], v[156:157] op_sel_hi:[0,1]
	v_pk_mul_f32 v[158:159], v[162:163], v[158:159] op_sel_hi:[0,1]
	v_pk_mul_f32 v[144:145], v[16:17], v[144:145]
	v_pk_mul_f32 v[146:147], v[18:19], v[146:147]
	v_pk_mul_f32 v[148:149], v[20:21], v[148:149]
	v_pk_mul_f32 v[150:151], v[22:23], v[150:151]
	v_pk_mul_f32 v[152:153], v[24:25], v[152:153]
	v_pk_mul_f32 v[154:155], v[26:27], v[154:155]
	v_pk_mul_f32 v[156:157], v[28:29], v[156:157]
	v_pk_mul_f32 v[158:159], v[30:31], v[158:159]
	v_pk_fma_f32 v[144:145], v[48:49], v[144:145], v[32:33]
	v_pk_fma_f32 v[146:147], v[50:51], v[146:147], v[34:35]
	v_pk_fma_f32 v[148:149], v[52:53], v[148:149], v[36:37]
	v_pk_fma_f32 v[150:151], v[54:55], v[150:151], v[38:39]
	v_pk_fma_f32 v[152:153], v[56:57], v[152:153], v[40:41]
	v_pk_fma_f32 v[154:155], v[58:59], v[154:155], v[42:43]
	v_pk_fma_f32 v[156:157], v[60:61], v[156:157], v[44:45]
	v_pk_fma_f32 v[158:159], v[62:63], v[158:159], v[46:47]
	v_cvt_pk_bf16_f32 v184, v144, v145
	v_cvt_pk_bf16_f32 v185, v146, v147
	v_cvt_pk_bf16_f32 v186, v148, v149
	v_cvt_pk_bf16_f32 v187, v150, v151
	v_cvt_pk_bf16_f32 v188, v152, v153
	v_cvt_pk_bf16_f32 v189, v154, v155
	v_cvt_pk_bf16_f32 v190, v156, v157
	v_cvt_pk_bf16_f32 v191, v158, v159
	s_add_i32 s10, s98, 0xd
	s_lshl_b32 s10, s10, 11
	s_add_u32 s28, s26, s10
	s_addc_u32 s29, s27, 0
	global_store_dwordx4 v2, v[184:187], s[28:29] sc1
	global_store_dwordx4 v2, v[188:191], s[28:29] offset:1024 sc1
	s_waitcnt vmcnt(12)
	ds_read_b128 v[32:35], v15 offset:0
	ds_read_b128 v[36:39], v15 offset:16
	ds_read_b128 v[40:43], v15 offset:2048
	ds_read_b128 v[44:47], v15 offset:2064
	ds_read_b128 v[48:51], v15 offset:32768
	ds_read_b128 v[52:55], v15 offset:32784
	ds_read_b128 v[56:59], v15 offset:34816
	ds_read_b128 v[60:63], v15 offset:34832
	v_lshlrev_b32_e32 v128, 16, v112
	v_and_b32_e32 v129, 0xffff0000, v112
	v_lshlrev_b32_e32 v130, 16, v113
	v_and_b32_e32 v131, 0xffff0000, v113
	v_lshlrev_b32_e32 v132, 16, v114
	v_and_b32_e32 v133, 0xffff0000, v114
	v_lshlrev_b32_e32 v134, 16, v115
	v_and_b32_e32 v135, 0xffff0000, v115
	v_lshlrev_b32_e32 v136, 16, v116
	v_and_b32_e32 v137, 0xffff0000, v116
	v_lshlrev_b32_e32 v138, 16, v117
	v_and_b32_e32 v139, 0xffff0000, v117
	v_lshlrev_b32_e32 v140, 16, v118
	v_and_b32_e32 v141, 0xffff0000, v118
	v_lshlrev_b32_e32 v142, 16, v119
	v_and_b32_e32 v143, 0xffff0000, v119
	v_lshlrev_b32_e32 v144, 16, v120
	v_and_b32_e32 v145, 0xffff0000, v120
	v_lshlrev_b32_e32 v146, 16, v121
	v_and_b32_e32 v147, 0xffff0000, v121
	v_lshlrev_b32_e32 v148, 16, v122
	v_and_b32_e32 v149, 0xffff0000, v122
	v_lshlrev_b32_e32 v150, 16, v123
	v_and_b32_e32 v151, 0xffff0000, v123
	v_lshlrev_b32_e32 v152, 16, v124
	v_and_b32_e32 v153, 0xffff0000, v124
	v_lshlrev_b32_e32 v154, 16, v125
	v_and_b32_e32 v155, 0xffff0000, v125
	v_lshlrev_b32_e32 v156, 16, v126
	v_and_b32_e32 v157, 0xffff0000, v126
	v_lshlrev_b32_e32 v158, 16, v127
	v_and_b32_e32 v159, 0xffff0000, v127
	v_pk_mul_f32 v[160:161], v[128:129], v[128:129]
	v_pk_mul_f32 v[162:163], v[144:145], v[144:145]
	v_pk_fma_f32 v[160:161], v[130:131], v[130:131], v[160:161]
	v_pk_fma_f32 v[162:163], v[146:147], v[146:147], v[162:163]
	v_pk_fma_f32 v[160:161], v[132:133], v[132:133], v[160:161]
	v_pk_fma_f32 v[162:163], v[148:149], v[148:149], v[162:163]
	v_pk_fma_f32 v[160:161], v[134:135], v[134:135], v[160:161]
	v_pk_fma_f32 v[162:163], v[150:151], v[150:151], v[162:163]
	v_pk_fma_f32 v[160:161], v[136:137], v[136:137], v[160:161]
	v_pk_fma_f32 v[162:163], v[152:153], v[152:153], v[162:163]
	v_pk_fma_f32 v[160:161], v[138:139], v[138:139], v[160:161]
	v_pk_fma_f32 v[162:163], v[154:155], v[154:155], v[162:163]
	v_pk_fma_f32 v[160:161], v[140:141], v[140:141], v[160:161]
	v_pk_fma_f32 v[162:163], v[156:157], v[156:157], v[162:163]
	v_pk_fma_f32 v[160:161], v[142:143], v[142:143], v[160:161]
	v_pk_fma_f32 v[162:163], v[158:159], v[158:159], v[162:163]
	v_add_f32_e32 v160, v160, v161
	v_add_f32_e32 v162, v162, v163
	ds_bpermute_b32 v164, v5, v160
	ds_bpermute_b32 v165, v5, v162
	s_waitcnt lgkmcnt(0)
	v_add_f32_e32 v160, v160, v164
	v_add_f32_e32 v162, v162, v165
	ds_bpermute_b32 v164, v6, v160
	ds_bpermute_b32 v165, v6, v162
	s_waitcnt lgkmcnt(0)
	v_add_f32_e32 v160, v160, v164
	v_add_f32_e32 v162, v162, v165
	ds_bpermute_b32 v164, v7, v160
	ds_bpermute_b32 v165, v7, v162
	s_waitcnt lgkmcnt(0)
	v_add_f32_e32 v160, v160, v164
	v_add_f32_e32 v162, v162, v165
	ds_bpermute_b32 v164, v9, v160
	ds_bpermute_b32 v165, v9, v162
	s_waitcnt lgkmcnt(0)
	v_add_f32_e32 v160, v160, v164
	v_add_f32_e32 v162, v162, v165
	ds_bpermute_b32 v164, v10, v160
	ds_bpermute_b32 v165, v10, v162
	s_waitcnt lgkmcnt(0)
	v_add_f32_e32 v160, v160, v164
	v_add_f32_e32 v162, v162, v165
	ds_bpermute_b32 v164, v11, v160
	ds_bpermute_b32 v165, v11, v162
	s_waitcnt lgkmcnt(0)
; __device__ __forceinline__ unsigned cvt_pk_bf16(float lo, float hi) { unsigned r; asm volatile("v_cvt_pk_bf16_f32 %0, %1, %2" : "=v"(r) : "v"(lo), "v"(hi)); return r; }
; __device__ __forceinline__ void norm_phase(const Params& P, unsigned char* ws, int layer, int which, int nrows, bool first, int lane, int wave, const float* pend_part, int pend_ns, const float* pend_gate) {
;     ...
;         for (int r = 0; r < NR; ++r) { const int row = row0 + r * NGW;
;             const float rstd = rsqrtf(wave_sum(ss[r], lane) * (1.0f / DM) + EPS);
;             const float* mod = (const float*)(ws + WS_MOD) + (size_t)(layer * 9 + (row >> 12)) * 6144 + which * 3 * DM;
; #pragma unroll
;             for (int j = 0; j < 2; ++j) { const int col = 8 * lane + 512 * j; u32x4 hw, xw;
; #pragma unroll
;                 for (int q = 0; q < 2; ++q) {
;                     const f32x4 g4 = *(const f32x4*)(g + col + 4 * q), sh = *(const f32x4*)(mod + col + 4 * q), sc = *(const f32x4*)(mod + DM + col + 4 * q);
;                     const f32x4 h = (v[r][j][q] * rstd) * g4 * (sc + 1.0f) + sh;
;                     if (q == 0) { hw.x = cvt_pk_bf16(h[0], h[1]); hw.y = cvt_pk_bf16(h[2], h[3]); xw.x = cvt_pk_bf16(v[r][j][q][0], v[r][j][q][1]); xw.y = cvt_pk_bf16(v[r][j][q][2], v[r][j][q][3]); }
;                     else { hw.z = cvt_pk_bf16(h[0], h[1]); hw.w = cvt_pk_bf16(h[2], h[3]); xw.z = cvt_pk_bf16(v[r][j][q][0], v[r][j][q][1]); xw.w = cvt_pk_bf16(v[r][j][q][2], v[r][j][q][3]); }
;                 }
;                 *(u32x4*)(H + (size_t)row * DM + col) = hw;
;                 if (first) *(u32x4*)(XB + (size_t)row * DM + col) = xw;
;             } }
	v_add_f32_e32 v160, v160, v164
	v_add_f32_e32 v162, v162, v165
	v_fmamk_f32 v160, v160, 0x3a800000, v194
	v_fmamk_f32 v162, v162, 0x3a800000, v194
	v_rsq_f32_e32 v160, v160
	v_rsq_f32_e32 v162, v162
	v_pk_add_f32 v[48:49], v[48:49], 1.0 op_sel_hi:[1,0]
	v_pk_add_f32 v[50:51], v[50:51], 1.0 op_sel_hi:[1,0]
	v_pk_add_f32 v[52:53], v[52:53], 1.0 op_sel_hi:[1,0]
	v_pk_add_f32 v[54:55], v[54:55], 1.0 op_sel_hi:[1,0]
	v_pk_add_f32 v[56:57], v[56:57], 1.0 op_sel_hi:[1,0]
	v_pk_add_f32 v[58:59], v[58:59], 1.0 op_sel_hi:[1,0]
	v_pk_add_f32 v[60:61], v[60:61], 1.0 op_sel_hi:[1,0]
	v_pk_add_f32 v[62:63], v[62:63], 1.0 op_sel_hi:[1,0]
	v_pk_mul_f32 v[128:129], v[160:161], v[128:129] op_sel_hi:[0,1]
	v_pk_mul_f32 v[130:131], v[160:161], v[130:131] op_sel_hi:[0,1]
	v_pk_mul_f32 v[132:133], v[160:161], v[132:133] op_sel_hi:[0,1]
	v_pk_mul_f32 v[134:135], v[160:161], v[134:135] op_sel_hi:[0,1]
	v_pk_mul_f32 v[136:137], v[160:161], v[136:137] op_sel_hi:[0,1]
	v_pk_mul_f32 v[138:139], v[160:161], v[138:139] op_sel_hi:[0,1]
	v_pk_mul_f32 v[140:141], v[160:161], v[140:141] op_sel_hi:[0,1]
	v_pk_mul_f32 v[142:143], v[160:161], v[142:143] op_sel_hi:[0,1]
	v_pk_mul_f32 v[128:129], v[16:17], v[128:129]
	v_pk_mul_f32 v[130:131], v[18:19], v[130:131]
	v_pk_mul_f32 v[132:133], v[20:21], v[132:133]
	v_pk_mul_f32 v[134:135], v[22:23], v[134:135]
	v_pk_mul_f32 v[136:137], v[24:25], v[136:137]
	v_pk_mul_f32 v[138:139], v[26:27], v[138:139]
	v_pk_mul_f32 v[140:141], v[28:29], v[140:141]
	v_pk_mul_f32 v[142:143], v[30:31], v[142:143]
	v_pk_fma_f32 v[128:129], v[48:49], v[128:129], v[32:33]
	v_pk_fma_f32 v[130:131], v[50:51], v[130:131], v[34:35]
	v_pk_fma_f32 v[132:133], v[52:53], v[132:133], v[36:37]
	v_pk_fma_f32 v[134:135], v[54:55], v[134:135], v[38:39]
	v_pk_fma_f32 v[136:137], v[56:57], v[136:137], v[40:41]
	v_pk_fma_f32 v[138:139], v[58:59], v[138:139], v[42:43]
	v_pk_fma_f32 v[140:141], v[60:61], v[140:141], v[44:45]
	v_pk_fma_f32 v[142:143], v[62:63], v[142:143], v[46:47]
	v_cvt_pk_bf16_f32 v176, v128, v129
	v_cvt_pk_bf16_f32 v177, v130, v131
	v_cvt_pk_bf16_f32 v178, v132, v133
	v_cvt_pk_bf16_f32 v179, v134, v135
	v_cvt_pk_bf16_f32 v180, v136, v137
	v_cvt_pk_bf16_f32 v181, v138, v139
	v_cvt_pk_bf16_f32 v182, v140, v141
	v_cvt_pk_bf16_f32 v183, v142, v143
	s_add_i32 s10, s98, 0xe
	s_lshl_b32 s10, s10, 11
	s_add_u32 s28, s26, s10
	s_addc_u32 s29, s27, 0
	global_store_dwordx4 v2, v[176:179], s[28:29] sc1
	global_store_dwordx4 v2, v[180:183], s[28:29] offset:1024 sc1
	v_pk_mul_f32 v[144:145], v[162:163], v[144:145] op_sel_hi:[0,1]
	v_pk_mul_f32 v[146:147], v[162:163], v[146:147] op_sel_hi:[0,1]
	v_pk_mul_f32 v[148:149], v[162:163], v[148:149] op_sel_hi:[0,1]
	v_pk_mul_f32 v[150:151], v[162:163], v[150:151] op_sel_hi:[0,1]
	v_pk_mul_f32 v[152:153], v[162:163], v[152:153] op_sel_hi:[0,1]
	v_pk_mul_f32 v[154:155], v[162:163], v[154:155] op_sel_hi:[0,1]
	v_pk_mul_f32 v[156:157], v[162:163], v[156:157] op_sel_hi:[0,1]
	v_pk_mul_f32 v[158:159], v[162:163], v[158:159] op_sel_hi:[0,1]
	v_pk_mul_f32 v[144:145], v[16:17], v[144:145]
	v_pk_mul_f32 v[146:147], v[18:19], v[146:147]
	v_pk_mul_f32 v[148:149], v[20:21], v[148:149]
	v_pk_mul_f32 v[150:151], v[22:23], v[150:151]
	v_pk_mul_f32 v[152:153], v[24:25], v[152:153]
	v_pk_mul_f32 v[154:155], v[26:27], v[154:155]
	v_pk_mul_f32 v[156:157], v[28:29], v[156:157]
	v_pk_mul_f32 v[158:159], v[30:31], v[158:159]
	v_pk_fma_f32 v[144:145], v[48:49], v[144:145], v[32:33]
	v_pk_fma_f32 v[146:147], v[50:51], v[146:147], v[34:35]
	v_pk_fma_f32 v[148:149], v[52:53], v[148:149], v[36:37]
	v_pk_fma_f32 v[150:151], v[54:55], v[150:151], v[38:39]
	v_pk_fma_f32 v[152:153], v[56:57], v[152:153], v[40:41]
	v_pk_fma_f32 v[154:155], v[58:59], v[154:155], v[42:43]
	v_pk_fma_f32 v[156:157], v[60:61], v[156:157], v[44:45]
	v_pk_fma_f32 v[158:159], v[62:63], v[158:159], v[46:47]
	v_cvt_pk_bf16_f32 v184, v144, v145
	v_cvt_pk_bf16_f32 v185, v146, v147
	v_cvt_pk_bf16_f32 v186, v148, v149
	v_cvt_pk_bf16_f32 v187, v150, v151
	v_cvt_pk_bf16_f32 v188, v152, v153
	v_cvt_pk_bf16_f32 v189, v154, v155
	v_cvt_pk_bf16_f32 v190, v156, v157
	v_cvt_pk_bf16_f32 v191, v158, v159
	s_add_i32 s10, s98, 0xf
	s_lshl_b32 s10, s10, 11
	s_add_u32 s28, s26, s10
	s_addc_u32 s29, s27, 0
	global_store_dwordx4 v2, v[184:187], s[28:29] sc1
	global_store_dwordx4 v2, v[188:191], s[28:29] offset:1024 sc1
	s_nop 1
	s_cmp_eq_u32 s99, 0
	s_cbranch_scc1 .LBB0_909
	s_branch .LBB0_951
.Lmy_n2_old:
	s_add_u32 s8, s20, 0x803000
	v_readlane_b32 s0, v253, 4
	v_readlane_b32 s1, v253, 51
	s_addc_u32 s9, s21, 0
	s_add_i32 s0, s0, s1
	s_ashr_i32 s1, s0, 31
	s_lshl_b64 s[0:1], s[0:1], 11
	s_add_u32 s3, s36, s0
	s_addc_u32 s10, s37, s1
	v_lshlrev_b32_e32 v0, 2, v221
	s_add_u32 s22, s64, s3
	v_readlane_b32 s48, v251, 10
	v_xor_b32_e32 v5, 4, v0
	v_xor_b32_e32 v9, 8, v0
	v_xor_b32_e32 v13, 16, v0
	s_waitcnt vmcnt(9)
	v_xor_b32_e32 v25, 32, v0
	s_waitcnt vmcnt(8)
	v_xor_b32_e32 v26, 64, v0
	v_xor_b32_e32 v27, 0x80, v0
	v_lshlrev_b32_e32 v0, 5, v221
	s_addc_u32 s23, s65, s10
	v_readlane_b32 s62, v251, 24
	v_lshl_add_u64 v[2:3], s[24:25], 0, v[0:1]
	v_readlane_b32 s63, v251, 25
	s_add_u32 s24, s62, s0
	s_addc_u32 s25, s63, s1
	s_ashr_i32 s3, s2, 31
	s_lshl_b64 s[0:1], s[2:3], 11
	s_add_u32 s3, s36, s0
	s_addc_u32 s10, s37, s1
	s_add_u32 s26, s64, s3
	v_lshlrev_b32_e32 v6, 3, v221
	s_addc_u32 s27, s65, s10
	v_or_b32_e32 v10, 0x200, v6
	s_add_u32 s28, s62, s0
	v_lshlrev_b32_e32 v0, 4, v221
	s_addc_u32 s29, s63, s1
	v_lshlrev_b32_e32 v28, 2, v6
	v_lshlrev_b32_e32 v29, 2, v10
	v_readlane_b32 s49, v251, 11
	v_readlane_b32 s50, v251, 12
	v_readlane_b32 s51, v251, 13
	v_readlane_b32 s52, v251, 14
	v_readlane_b32 s53, v251, 15
	v_readlane_b32 s54, v251, 16
	v_readlane_b32 s55, v251, 17
	v_readlane_b32 s56, v251, 18
	v_readlane_b32 s57, v251, 19
	v_readlane_b32 s58, v251, 20
	v_readlane_b32 s59, v251, 21
	v_readlane_b32 s60, v251, 22
	v_readlane_b32 s61, v251, 23

; __device__ __forceinline__ f32x4 bf4_to_f32(u32x2 w) { return (f32x4){__builtin_bit_cast(float, w.x << 16), __builtin_bit_cast(float, w.x & 0xffff0000u), __builtin_bit_cast(float, w.y << 16), __builtin_bit_cast(float, w.y & 0xffff0000u)}; }
; __device__ __forceinline__ void norm_phase(const Params& P, unsigned char* ws, int layer, int which, int nrows, bool first, int lane, int wave, const float* pend_part, int pend_ns, const float* pend_gate) {
;     ...
;     for (int row0 = gw; row0 < MLAT; row0 += NR * NGW) {
;         f32x4 v[NR][2][2]; float ss[NR];
; #pragma unroll
;         for (int r = 0; r < NR; ++r) { const int row = row0 + r * NGW; ss[r] = 0.f;
; #pragma unroll
;             for (int j = 0; j < 2; ++j) { const int col = 8 * lane + 512 * j;
;                 if (first) { v[r][j][0] = *(const f32x4*)(P.in[I_X] + (size_t)row * DM + col); v[r][j][1] = *(const f32x4*)(P.in[I_X] + (size_t)row * DM + col + 4); }
;                 else { const u32x4 w = *(const u32x4*)(XB + (size_t)row * DM + col); v[r][j][0] = bf4_to_f32((u32x2){w.x, w.y}); v[r][j][1] = bf4_to_f32((u32x2){w.z, w.w}); } } }
; __global__ void __launch_bounds__(NTHR, 2) fwd_megakernel(Params P) {
;     ...
;         else if (type == PH_NORM1) norm_phase(P, ws, layer, 0, MTOT, layer == 0, lane, wave, (const float*)(ws + PART_FFN2), layer > 0 ? NS_FFN2 : 0, (const float*)(ws + WS_MOD) + (size_t)((layer > 0 ? layer - 1 : 0) * 9 + 8) * 6144 + 5 * DM);
.LBB0_924:
	s_cmpk_gt_i32 s24, 0x7fff
	s_cbranch_scc1 .LBB0_951
	s_cmp_eq_u32 s88, 0x800
	s_cbranch_scc0 .Lmy_n1_old
	s_and_b64 vcc, exec, s[22:23]
	s_cbranch_vccz .Lmy_n1_old
	s_mov_b32 s2, s24
	s_mov_b64 s[24:25], s[26:27]
	s_add_u32 s8, s20, 0x800000
	s_addc_u32 s9, s21, 0
	s_mov_b32 s99, 1
	s_branch .Lmy_norm_entry
.Lmy_n1_old:
	s_add_u32 s8, s20, 0x800000
	v_mov_b32_e32 v3, v1
	s_addc_u32 s9, s21, 0
	s_waitcnt vmcnt(11)
	v_lshl_add_u64 v[14:15], s[20:21], 0, v[2:3]
	s_mov_b64 s[0:1], 0x6400000
	s_ashr_i32 s25, s24, 31
	v_lshl_add_u64 v[48:49], v[14:15], 0, s[0:1]
	s_lshl_b64 s[0:1], s[24:25], 11
	v_lshlrev_b32_e32 v0, 2, v221
	s_add_u32 s10, s36, s0
	v_xor_b32_e32 v5, 4, v0
	v_xor_b32_e32 v7, 8, v0
	v_xor_b32_e32 v9, 16, v0
	v_xor_b32_e32 v11, 32, v0
	v_xor_b32_e32 v13, 64, v0
	v_xor_b32_e32 v56, 0x80, v0
	v_lshlrev_b32_e32 v0, 5, v221
	s_addc_u32 s13, s37, s1
	v_lshl_add_u64 v[46:47], s[26:27], 0, v[0:1]
	s_add_u32 s26, s64, s10
	v_readlane_b32 s48, v251, 10
	s_addc_u32 s27, s65, s13
	v_readlane_b32 s62, v251, 24
	v_readlane_b32 s63, v251, 25
	s_add_u32 s28, s62, s0
	s_addc_u32 s29, s63, s1
	s_lshl_b64 s[0:1], s[24:25], 12
	v_readlane_b32 s10, v253, 5
	s_add_u32 s0, s10, s0
	v_readlane_b32 s10, v253, 6
	v_lshlrev_b32_e32 v6, 3, v221
	s_addc_u32 s1, s10, s1
	v_or_b32_e32 v10, 0x200, v6
	v_lshl_add_u64 v[50:51], s[0:1], 0, v[0:1]
	v_readlane_b32 s49, v251, 11
	v_readlane_b32 s50, v251, 12
	v_readlane_b32 s51, v251, 13
	v_readlane_b32 s52, v251, 14
	v_readlane_b32 s53, v251, 15
	v_readlane_b32 s54, v251, 16
	v_readlane_b32 s55, v251, 17
	v_readlane_b32 s56, v251, 18
	v_readlane_b32 s57, v251, 19
	v_readlane_b32 s58, v251, 20
	v_readlane_b32 s59, v251, 21
	v_readlane_b32 s60, v251, 22
	v_readlane_b32 s61, v251, 23
	s_branch .LBB0_927
